# input-projection epilogue: rope table entries of the next row group prefetched into two register sets with counted waits
# baseline (speedup 1.0000x reference)
; template <int N4> __device__ __forceinline__ float sum_parts(const float* p) {
;     f32x4 a = *(const f32x4*)p;
; #pragma unroll
;     for (int i = 1; i < N4; ++i) a += *(const f32x4*)(p + 4 * i);
;     return (a[0] + a[1]) + (a[2] + a[3]);
;     __device__ __forceinline__ void operator()(const f32x4 (&acc)[2][2][4][2], const Unit& u, int wr, int wc, int fr, int fq) const {
;     ...
;         for (int ai = 0; ai < 2; ++ai)
; #pragma unroll
;             for (int m = 0; m < 4; ++m) {
;                 const int row = row0 + ai * HALF + m * 16;
;                 const float r = __builtin_amdgcn_rsqf(sum_parts<8>(ssq_h + (size_t)row * 32) * (1.0f / 2048.0f) + 1e-6f);
; #pragma unroll
;                 for (int bj = 0; bj < 2; ++bj) {
;                     float v[8];
; #pragma unroll
;                     for (int e = 0; e < 4; ++e) { v[e] = acc[ai][bj][m][0][e] * r; v[4 + e] = acc[ai][bj][m][1][e] * r; }
;                     if (tab[bj] >= 0) rope8(v, TAB + (size_t)row * NTAB + tab[bj]);
.LBB0_343:
	s_ashr_i32 s1, s1, 2
	s_andn2_b32 s1, s1, 63
	v_lshrrev_b32_e32 v198, 4, v146
	v_and_or_b32 v146, v146, 15, s1
	v_lshl_add_u32 v146, s87, 8, v146
	v_ashrrev_i32_e32 v147, 31, v146
	v_lshlrev_b32_e32 v198, 5, v198
	v_mov_b32_e32 v199, 0
	v_lshlrev_b64 v[190:191], 7, v[146:147]
	v_lshl_add_u64 v[190:191], s[22:23], 0, v[190:191]
	v_lshl_add_u64 v[190:191], v[190:191], 0, v[198:199]
	v_mov_b32_e32 v160, 0x1000
	v_mov_b32_e32 v161, 0
	v_lshl_add_u64 v[192:193], v[160:161], 0, v[190:191]
	v_lshl_add_u64 v[194:195], v[160:161], 2, v[190:191]
	v_lshl_add_u64 v[196:197], v[160:161], 0, v[194:195]
	global_load_dwordx4 v[218:221], v[190:191], off
	global_load_dwordx4 v[222:225], v[190:191], off offset:16
	global_load_dwordx4 v[226:229], v[190:191], off offset:2048
	global_load_dwordx4 v[230:233], v[190:191], off offset:2064
	global_load_dwordx4 v[234:237], v[192:193], off
	global_load_dwordx4 v[238:241], v[192:193], off offset:16
	global_load_dwordx4 v[178:181], v[192:193], off offset:2048
	global_load_dwordx4 v[182:185], v[192:193], off offset:2064
	global_load_dwordx4 v[186:189], v[194:195], off
	global_load_dwordx4 v[154:157], v[194:195], off offset:16
	global_load_dwordx4 v[160:163], v[194:195], off offset:2048
	global_load_dwordx4 v[164:167], v[194:195], off offset:2064
	global_load_dwordx4 v[242:245], v[196:197], off
	global_load_dwordx4 v[246:249], v[196:197], off offset:16
	global_load_dwordx4 v[250:253], v[196:197], off offset:2048
	global_load_dwordx4 v[206:209], v[196:197], off offset:2064
	s_waitcnt vmcnt(0)
	v_pk_add_f32 v[218:219], v[218:219], v[220:221]
	v_pk_add_f32 v[222:223], v[222:223], v[224:225]
	v_pk_add_f32 v[218:219], v[218:219], v[222:223]
	v_add_f32_e32 v168, v218, v219
	v_pk_add_f32 v[226:227], v[226:227], v[228:229]
	v_pk_add_f32 v[230:231], v[230:231], v[232:233]
	v_pk_add_f32 v[226:227], v[226:227], v[230:231]
	v_add_f32_e32 v169, v226, v227
	v_pk_add_f32 v[234:235], v[234:235], v[236:237]
	v_pk_add_f32 v[238:239], v[238:239], v[240:241]
	v_pk_add_f32 v[234:235], v[234:235], v[238:239]
	v_add_f32_e32 v170, v234, v235
	v_pk_add_f32 v[178:179], v[178:179], v[180:181]
	v_pk_add_f32 v[182:183], v[182:183], v[184:185]
	v_pk_add_f32 v[178:179], v[178:179], v[182:183]
	v_add_f32_e32 v171, v178, v179
	v_pk_add_f32 v[186:187], v[186:187], v[188:189]
	v_pk_add_f32 v[154:155], v[154:155], v[156:157]
	v_pk_add_f32 v[186:187], v[186:187], v[154:155]
	v_add_f32_e32 v172, v186, v187
	v_pk_add_f32 v[160:161], v[160:161], v[162:163]
	v_pk_add_f32 v[164:165], v[164:165], v[166:167]
	v_pk_add_f32 v[160:161], v[160:161], v[164:165]
	v_add_f32_e32 v173, v160, v161
	v_pk_add_f32 v[242:243], v[242:243], v[244:245]
	v_pk_add_f32 v[246:247], v[246:247], v[248:249]
	v_pk_add_f32 v[242:243], v[242:243], v[246:247]
	v_add_f32_e32 v174, v242, v243
	v_pk_add_f32 v[250:251], v[250:251], v[252:253]
	v_pk_add_f32 v[206:207], v[206:207], v[208:209]
	v_pk_add_f32 v[250:251], v[250:251], v[206:207]
	v_add_f32_e32 v175, v250, v251
	v_mov_b32_e32 v234, v168
	v_mov_b32_e32 v235, v169
	v_mov_b32_e32 v236, v170
	v_mov_b32_e32 v237, v171
	v_mov_b32_e32 v238, v172
	v_mov_b32_e32 v239, v173
	v_mov_b32_e32 v240, v174
	v_mov_b32_e32 v241, v175
	v_permlane32_swap_b32_e32 v168, v234
	v_permlane32_swap_b32_e32 v169, v235
	v_permlane32_swap_b32_e32 v170, v236
	v_permlane32_swap_b32_e32 v171, v237
	v_permlane32_swap_b32_e32 v172, v238
	v_permlane32_swap_b32_e32 v173, v239
	v_permlane32_swap_b32_e32 v174, v240
	v_permlane32_swap_b32_e32 v175, v241
	v_add_f32_e32 v168, v168, v234
	v_add_f32_e32 v169, v169, v235
	v_add_f32_e32 v170, v170, v236
	v_add_f32_e32 v171, v171, v237
	v_add_f32_e32 v172, v172, v238
	v_add_f32_e32 v173, v173, v239
	v_add_f32_e32 v174, v174, v240
	v_add_f32_e32 v175, v175, v241
	v_mov_b32_e32 v234, v168
	v_mov_b32_e32 v235, v169
	v_mov_b32_e32 v236, v170
	v_mov_b32_e32 v237, v171
	v_mov_b32_e32 v238, v172
	v_mov_b32_e32 v239, v173
	v_mov_b32_e32 v240, v174
	v_mov_b32_e32 v241, v175
	v_permlane16_swap_b32_e32 v168, v234
	v_permlane16_swap_b32_e32 v169, v235
	v_permlane16_swap_b32_e32 v170, v236
	v_permlane16_swap_b32_e32 v171, v237
	v_permlane16_swap_b32_e32 v172, v238
	v_permlane16_swap_b32_e32 v173, v239
	v_permlane16_swap_b32_e32 v174, v240
	v_permlane16_swap_b32_e32 v175, v241
	v_add_f32_e32 v168, v168, v234
	v_add_f32_e32 v169, v169, v235
	v_add_f32_e32 v170, v170, v236
	v_add_f32_e32 v171, v171, v237
	v_add_f32_e32 v172, v172, v238
	v_add_f32_e32 v173, v173, v239
	v_add_f32_e32 v174, v174, v240
	v_add_f32_e32 v175, v175, v241
	v_fmamk_f32 v168, v168, 0x3a000000, v204
	v_fmamk_f32 v169, v169, 0x3a000000, v204
	v_fmamk_f32 v170, v170, 0x3a000000, v204
	v_fmamk_f32 v171, v171, 0x3a000000, v204
	v_fmamk_f32 v172, v172, 0x3a000000, v204
	v_fmamk_f32 v173, v173, 0x3a000000, v204
	v_fmamk_f32 v174, v174, 0x3a000000, v204
	v_fmamk_f32 v175, v175, 0x3a000000, v204
	v_rsq_f32_e32 v168, v168
	v_rsq_f32_e32 v169, v169
	v_rsq_f32_e32 v170, v170
	v_rsq_f32_e32 v171, v171
	v_rsq_f32_e32 v172, v172
	v_rsq_f32_e32 v173, v173
	v_rsq_f32_e32 v174, v174
	v_rsq_f32_e32 v175, v175
	v_mov_b32_e32 v216, 0x1c0
	v_mad_i64_i32 v[210:211], s[100:101], v146, v216, 0
	v_lshl_add_u64 v[210:211], s[70:71], 0, v[210:211]
	v_max_i32_e32 v216, 0, v0
	v_mov_b32_e32 v217, 0
	v_lshl_add_u64 v[212:213], v[216:217], 3, v[210:211]
	v_max_i32_e32 v216, 0, v144
	v_lshl_add_u64 v[210:211], v[216:217], 3, v[210:211]
	global_load_dwordx4 v[222:225], v[212:213], off offset:16
	global_load_dwordx4 v[218:221], v[212:213], off
	global_load_dwordx4 v[230:233], v[210:211], off offset:16
	global_load_dwordx4 v[226:229], v[210:211], off
	s_movk_i32 s1, 0x1c0
	v_mad_i64_i32 v[156:157], s[6:7], v146, s1, 0
	v_mov_b32_e32 v154, v168
	v_cmp_lt_i32_e64 s[6:7], -1, v0
	v_lshl_add_u64 v[156:157], s[70:71], 0, v[156:157]
	v_pk_mul_f32 v[2:3], v[2:3], v[154:155] op_sel_hi:[1,0]
	v_pk_mul_f32 v[6:7], v[6:7], v[154:155] op_sel_hi:[1,0]
	v_pk_mul_f32 v[4:5], v[4:5], v[154:155] op_sel_hi:[1,0]
	v_pk_mul_f32 v[8:9], v[8:9], v[154:155] op_sel_hi:[1,0]
	s_and_saveexec_b64 s[8:9], s[6:7]
	s_cbranch_execz .LBB0_345
; __device__ __forceinline__ void rope8(float (&v)[8], const tab_t* tp) {
;     const f32x4 t0 = *(const f32x4*)tp, t1 = *(const f32x4*)(tp + 2);
;     const float c[4] = {t0[0], t0[2], t1[0], t1[2]}, s[4] = {t0[1], t0[3], t1[1], t1[3]};
; #pragma unroll
;     for (int j = 0; j < 4; ++j) { const float a = v[2 * j], b = v[2 * j + 1]; v[2 * j] = a * c[j] - b * s[j]; v[2 * j + 1] = b * c[j] + a * s[j]; }
; }
	s_waitcnt vmcnt(2)
	v_pk_mul_f32 v[160:161], v[2:3], v[218:219] op_sel:[1, 1] op_sel_hi:[1, 0]
	s_nop 0
	v_pk_fma_f32 v[178:179], v[2:3], v[218:219], v[160:161] op_sel_hi:[0, 1, 1] neg_lo:[0, 0, 1] neg_hi:[0, 0, 1]
	v_pk_fma_f32 v[2:3], v[2:3], v[218:219], v[160:161] op_sel_hi:[0, 1, 1]
	v_pk_mul_f32 v[160:161], v[4:5], v[220:221] op_sel:[1, 1] op_sel_hi:[1, 0]
	v_mul_f32_e32 v2, v9, v225
	v_pk_fma_f32 v[180:181], v[4:5], v[220:221], v[160:161] op_sel_hi:[0, 1, 1] neg_lo:[0, 0, 1] neg_hi:[0, 0, 1]
	v_pk_fma_f32 v[4:5], v[4:5], v[220:221], v[160:161] op_sel_hi:[0, 1, 1]
	v_pk_mul_f32 v[160:161], v[6:7], v[222:223] op_sel:[1, 1] op_sel_hi:[1, 0]
	v_mov_b32_e32 v179, v3
	v_pk_fma_f32 v[182:183], v[6:7], v[222:223], v[160:161] op_sel_hi:[0, 1, 1] neg_lo:[0, 0, 1] neg_hi:[0, 0, 1]
	v_pk_fma_f32 v[6:7], v[6:7], v[222:223], v[160:161] op_sel_hi:[0, 1, 1]
	v_pk_fma_f32 v[184:185], v[8:9], v[224:225], v[2:3] op_sel_hi:[1, 1, 0] neg_lo:[0, 0, 1] neg_hi:[0, 0, 1]
	v_mul_f32_e32 v2, v9, v224
	v_pk_fma_f32 v[8:9], v[8:9], v[224:225], v[2:3] op_sel:[0, 1, 0] op_sel_hi:[1, 0, 0]
	v_mov_b32_e32 v181, v5
	v_mov_b32_e32 v183, v7
	v_mov_b32_e32 v185, v8
	v_mov_b64_e32 v[2:3], v[178:179]
	v_mov_b64_e32 v[4:5], v[180:181]
	v_mov_b64_e32 v[6:7], v[182:183]
	v_mov_b64_e32 v[8:9], v[184:185]

; __device__ __forceinline__ float silu_f(float x) { return x * __builtin_amdgcn_rcpf(1.0f + __builtin_amdgcn_exp2f(-x * 1.4426950408889634f)); }
; __device__ __forceinline__ void rope8(float (&v)[8], const tab_t* tp) {
;     const f32x4 t0 = *(const f32x4*)tp, t1 = *(const f32x4*)(tp + 2);
;     const float c[4] = {t0[0], t0[2], t1[0], t1[2]}, s[4] = {t0[1], t0[3], t1[1], t1[3]};
; #pragma unroll
;     for (int j = 0; j < 4; ++j) { const float a = v[2 * j], b = v[2 * j + 1]; v[2 * j] = a * c[j] - b * s[j]; v[2 * j + 1] = b * c[j] + a * s[j]; }
; }
;     __device__ __forceinline__ void operator()(const f32x4 (&acc)[2][2][4][2], const Unit& u, int wr, int wc, int fr, int fq) const {
;     ...
;                     for (int e = 0; e < 4; ++e) { v[e] = acc[ai][bj][m][0][e] * r; v[4 + e] = acc[ai][bj][m][1][e] * r; }
;                     if (tab[bj] >= 0) rope8(v, TAB + (size_t)row * NTAB + tab[bj]);
;                     if (act[bj]) {
; #pragma unroll
;                         for (int e = 0; e < 8; ++e) v[e] = silu_f(v[e]);
;                     }
; #pragma unroll
;                     for (int e = 0; e < 8; ++e) v[e] *= sc[bj];
;                     if (ssq[bj]) { float s = 0.f;
; #pragma unroll
;                         for (int e = 0; e < 8; ++e) s += v[e] * v[e];
;                         s += __shfl_xor(s, 16); s += __shfl_xor(s, 32);
;                         if (fq == 0) ssq[bj][(size_t)row * sld[bj]] = s; }
;                     store8(dst[bj] + (size_t)row * ld[bj], v);
.LBB0_351:
	v_ashrrev_i32_e32 v149, 31, v148
	v_lshl_add_u64 v[148:149], v[148:149], 1, s[10:11]
	v_mul_lo_u32 v7, s91, v146
	v_mul_lo_u32 v160, s90, v147
	s_waitcnt lgkmcnt(0)
	v_mad_u64_u32 v[8:9], s[10:11], s90, v146, 0
	v_add3_u32 v9, v9, v160, v7
	v_lshl_add_u64 v[8:9], v[8:9], 1, v[148:149]
	v_cvt_pk_bf16_f32 v178, v145, v178
	v_cvt_pk_bf16_f32 v179, v4, v151
	v_cvt_pk_bf16_f32 v180, v3, v5
	v_cvt_pk_bf16_f32 v181, v2, v6
	v_mov_b32_e32 v252, 0x1c00
	v_mov_b32_e32 v253, 0
	v_lshl_add_u64 v[250:251], v[252:253], 0, v[212:213]
	global_load_dwordx4 v[238:241], v[250:251], off offset:16
	global_load_dwordx4 v[234:237], v[250:251], off
	v_lshl_add_u64 v[250:251], v[252:253], 0, v[210:211]
	global_load_dwordx4 v[246:249], v[250:251], off offset:16
	global_load_dwordx4 v[242:245], v[250:251], off
	global_store_dwordx4 v[8:9], v[178:181], off
	v_mov_b32_e32 v155, v154
	v_pk_mul_f32 v[2:3], v[126:127], v[154:155]
	v_pk_mul_f32 v[6:7], v[122:123], v[154:155]
	v_pk_mul_f32 v[4:5], v[128:129], v[154:155]
	v_pk_mul_f32 v[8:9], v[124:125], v[154:155]
	v_cmp_lt_i32_e64 s[10:11], -1, v144
	s_and_saveexec_b64 s[14:15], s[10:11]
	s_cbranch_execz .LBB0_353
	v_mov_b32_e32 v145, v1
	s_waitcnt vmcnt(5)
	v_pk_mul_f32 v[128:129], v[2:3], v[226:227] op_sel:[1, 1] op_sel_hi:[1, 0]
	s_nop 0
	v_pk_fma_f32 v[122:123], v[2:3], v[226:227], v[128:129] op_sel_hi:[0, 1, 1] neg_lo:[0, 0, 1] neg_hi:[0, 0, 1]
	v_pk_fma_f32 v[2:3], v[2:3], v[226:227], v[128:129] op_sel_hi:[0, 1, 1]
	v_pk_mul_f32 v[128:129], v[4:5], v[228:229] op_sel:[1, 1] op_sel_hi:[1, 0]
	v_mul_f32_e32 v2, v9, v233
	v_pk_fma_f32 v[124:125], v[4:5], v[228:229], v[128:129] op_sel_hi:[0, 1, 1] neg_lo:[0, 0, 1] neg_hi:[0, 0, 1]
	v_pk_fma_f32 v[4:5], v[4:5], v[228:229], v[128:129] op_sel_hi:[0, 1, 1]
	v_pk_mul_f32 v[128:129], v[6:7], v[230:231] op_sel:[1, 1] op_sel_hi:[1, 0]
	v_mov_b32_e32 v123, v3
	v_pk_fma_f32 v[126:127], v[6:7], v[230:231], v[128:129] op_sel_hi:[0, 1, 1] neg_lo:[0, 0, 1] neg_hi:[0, 0, 1]
	v_pk_fma_f32 v[6:7], v[6:7], v[230:231], v[128:129] op_sel_hi:[0, 1, 1]
	v_pk_fma_f32 v[128:129], v[8:9], v[232:233], v[2:3] op_sel_hi:[1, 1, 0] neg_lo:[0, 0, 1] neg_hi:[0, 0, 1]
	v_mul_f32_e32 v2, v9, v232
	v_pk_fma_f32 v[8:9], v[8:9], v[232:233], v[2:3] op_sel:[0, 1, 0] op_sel_hi:[1, 0, 0]
	v_mov_b32_e32 v125, v5
	v_mov_b32_e32 v127, v7
	v_mov_b32_e32 v129, v8
	v_mov_b64_e32 v[2:3], v[122:123]
	v_mov_b64_e32 v[4:5], v[124:125]
	v_mov_b64_e32 v[6:7], v[126:127]
	v_mov_b64_e32 v[8:9], v[128:129]

; __device__ __forceinline__ float silu_f(float x) { return x * __builtin_amdgcn_rcpf(1.0f + __builtin_amdgcn_exp2f(-x * 1.4426950408889634f)); }
; __device__ __forceinline__ void rope8(float (&v)[8], const tab_t* tp) {
;     const f32x4 t0 = *(const f32x4*)tp, t1 = *(const f32x4*)(tp + 2);
;     const float c[4] = {t0[0], t0[2], t1[0], t1[2]}, s[4] = {t0[1], t0[3], t1[1], t1[3]};
; #pragma unroll
;     for (int j = 0; j < 4; ++j) { const float a = v[2 * j], b = v[2 * j + 1]; v[2 * j] = a * c[j] - b * s[j]; v[2 * j + 1] = b * c[j] + a * s[j]; }
; }
;     __device__ __forceinline__ void operator()(const f32x4 (&acc)[2][2][4][2], const Unit& u, int wr, int wc, int fr, int fq) const {
;     ...
;                 const int row = row0 + ai * HALF + m * 16;
;                 const float r = __builtin_amdgcn_rsqf(sum_parts<8>(ssq_h + (size_t)row * 32) * (1.0f / 2048.0f) + 1e-6f);
; #pragma unroll
;                 for (int bj = 0; bj < 2; ++bj) {
;                     float v[8];
; #pragma unroll
;                     for (int e = 0; e < 4; ++e) { v[e] = acc[ai][bj][m][0][e] * r; v[4 + e] = acc[ai][bj][m][1][e] * r; }
;                     if (tab[bj] >= 0) rope8(v, TAB + (size_t)row * NTAB + tab[bj]);
;                     if (act[bj]) {
; #pragma unroll
;                         for (int e = 0; e < 8; ++e) v[e] = silu_f(v[e]);
;                     }
; #pragma unroll
;                     for (int e = 0; e < 8; ++e) v[e] *= sc[bj];
;                     if (ssq[bj]) { float s = 0.f;
; #pragma unroll
;                         for (int e = 0; e < 8; ++e) s += v[e] * v[e];
;                         s += __shfl_xor(s, 16); s += __shfl_xor(s, 32);
;                         if (fq == 0) ssq[bj][(size_t)row * sld[bj]] = s; }
;                     store8(dst[bj] + (size_t)row * ld[bj], v);
.LBB0_359:
	v_ashrrev_i32_e32 v151, 31, v150
	v_mul_lo_u32 v8, s93, v146
	v_mul_lo_u32 v9, s92, v147
	s_waitcnt lgkmcnt(0)
	v_mad_u64_u32 v[6:7], s[14:15], s92, v146, 0
	v_lshl_add_u64 v[122:123], v[150:151], 1, v[152:153]
	v_add3_u32 v7, v7, v9, v8
	v_lshl_add_u64 v[128:129], v[6:7], 1, v[122:123]
	v_cvt_pk_bf16_f32 v6, v125, v127
	v_cvt_pk_bf16_f32 v7, v124, v126
	v_or_b32_e32 v124, 16, v146
	v_ashrrev_i32_e32 v125, 31, v124
	v_cvt_pk_bf16_f32 v8, v3, v5
	v_cvt_pk_bf16_f32 v9, v2, v4
	global_store_dwordx4 v[128:129], v[6:9], off
	v_mad_i64_i32 v[128:129], s[14:15], v124, s1, 0
	v_mov_b32_e32 v126, v169
	s_nop 0
	v_pk_mul_f32 v[2:3], v[118:119], v[126:127] op_sel_hi:[1,0]
	v_pk_mul_f32 v[6:7], v[114:115], v[126:127] op_sel_hi:[1,0]
	v_pk_mul_f32 v[4:5], v[120:121], v[126:127] op_sel_hi:[1,0]
	v_pk_mul_f32 v[8:9], v[116:117], v[126:127] op_sel_hi:[1,0]
	v_lshl_add_u64 v[114:115], s[70:71], 0, v[128:129]
	s_and_saveexec_b64 s[14:15], s[6:7]
	s_cbranch_execz .LBB0_361
	s_waitcnt vmcnt(4)
	v_pk_mul_f32 v[120:121], v[2:3], v[234:235] op_sel:[1, 1] op_sel_hi:[1, 0]
	s_nop 0
	v_pk_fma_f32 v[150:151], v[2:3], v[234:235], v[120:121] op_sel_hi:[0, 1, 1] neg_lo:[0, 0, 1] neg_hi:[0, 0, 1]
	v_pk_fma_f32 v[2:3], v[2:3], v[234:235], v[120:121] op_sel_hi:[0, 1, 1]
	v_pk_mul_f32 v[120:121], v[4:5], v[236:237] op_sel:[1, 1] op_sel_hi:[1, 0]
	v_mul_f32_e32 v2, v9, v241
	v_pk_fma_f32 v[152:153], v[4:5], v[236:237], v[120:121] op_sel_hi:[0, 1, 1] neg_lo:[0, 0, 1] neg_hi:[0, 0, 1]
	v_pk_fma_f32 v[4:5], v[4:5], v[236:237], v[120:121] op_sel_hi:[0, 1, 1]
	v_pk_mul_f32 v[120:121], v[6:7], v[238:239] op_sel:[1, 1] op_sel_hi:[1, 0]
	v_pk_fma_f32 v[156:157], v[8:9], v[240:241], v[2:3] op_sel_hi:[1, 1, 0] neg_lo:[0, 0, 1] neg_hi:[0, 0, 1]
	v_mul_f32_e32 v2, v9, v240
	v_pk_fma_f32 v[154:155], v[6:7], v[238:239], v[120:121] op_sel_hi:[0, 1, 1] neg_lo:[0, 0, 1] neg_hi:[0, 0, 1]
	v_pk_fma_f32 v[6:7], v[6:7], v[238:239], v[120:121] op_sel_hi:[0, 1, 1]
	v_pk_fma_f32 v[8:9], v[8:9], v[240:241], v[2:3] op_sel:[0, 1, 0] op_sel_hi:[1, 0, 0]
	v_mov_b32_e32 v151, v3
	v_mov_b32_e32 v153, v5
	v_mov_b32_e32 v155, v7
	v_mov_b32_e32 v157, v8
	v_mov_b64_e32 v[2:3], v[150:151]
	v_mov_b64_e32 v[4:5], v[152:153]
	v_mov_b64_e32 v[6:7], v[154:155]
	v_mov_b64_e32 v[8:9], v[156:157]

; __device__ __forceinline__ float silu_f(float x) { return x * __builtin_amdgcn_rcpf(1.0f + __builtin_amdgcn_exp2f(-x * 1.4426950408889634f)); }
; __device__ __forceinline__ void rope8(float (&v)[8], const tab_t* tp) {
;     const f32x4 t0 = *(const f32x4*)tp, t1 = *(const f32x4*)(tp + 2);
;     const float c[4] = {t0[0], t0[2], t1[0], t1[2]}, s[4] = {t0[1], t0[3], t1[1], t1[3]};
; #pragma unroll
;     for (int j = 0; j < 4; ++j) { const float a = v[2 * j], b = v[2 * j + 1]; v[2 * j] = a * c[j] - b * s[j]; v[2 * j + 1] = b * c[j] + a * s[j]; }
; }
;     __device__ __forceinline__ void operator()(const f32x4 (&acc)[2][2][4][2], const Unit& u, int wr, int wc, int fr, int fq) const {
;     ...
;                     for (int e = 0; e < 4; ++e) { v[e] = acc[ai][bj][m][0][e] * r; v[4 + e] = acc[ai][bj][m][1][e] * r; }
;                     if (tab[bj] >= 0) rope8(v, TAB + (size_t)row * NTAB + tab[bj]);
;                     if (act[bj]) {
; #pragma unroll
;                         for (int e = 0; e < 8; ++e) v[e] = silu_f(v[e]);
;                     }
; #pragma unroll
;                     for (int e = 0; e < 8; ++e) v[e] *= sc[bj];
;                     if (ssq[bj]) { float s = 0.f;
; #pragma unroll
;                         for (int e = 0; e < 8; ++e) s += v[e] * v[e];
;                         s += __shfl_xor(s, 16); s += __shfl_xor(s, 32);
;                         if (fq == 0) ssq[bj][(size_t)row * sld[bj]] = s; }
;                     store8(dst[bj] + (size_t)row * ld[bj], v);
.LBB0_367:
	v_mul_lo_u32 v7, s91, v124
	v_mul_lo_u32 v119, s90, v125
	s_waitcnt lgkmcnt(0)
	v_mad_u64_u32 v[8:9], s[16:17], s90, v124, 0
	v_add3_u32 v9, v9, v119, v7
	v_lshl_add_u64 v[8:9], v[8:9], 1, v[148:149]
	v_cvt_pk_bf16_f32 v116, v116, v118
	v_cvt_pk_bf16_f32 v117, v4, v117
	v_cvt_pk_bf16_f32 v118, v3, v5
	v_cvt_pk_bf16_f32 v119, v2, v6
	v_mov_b32_e32 v252, 0x3800
	v_mov_b32_e32 v253, 0
	v_lshl_add_u64 v[250:251], v[252:253], 0, v[212:213]
	global_load_dwordx4 v[222:225], v[250:251], off offset:16
	global_load_dwordx4 v[218:221], v[250:251], off
	v_lshl_add_u64 v[250:251], v[252:253], 0, v[210:211]
	global_load_dwordx4 v[230:233], v[250:251], off offset:16
	global_load_dwordx4 v[226:229], v[250:251], off
	global_store_dwordx4 v[8:9], v[116:119], off
	v_mov_b32_e32 v127, v126
	v_pk_mul_f32 v[2:3], v[110:111], v[126:127]
	v_pk_mul_f32 v[6:7], v[106:107], v[126:127]
	v_pk_mul_f32 v[4:5], v[112:113], v[126:127]
	v_pk_mul_f32 v[8:9], v[108:109], v[126:127]
	s_and_saveexec_b64 s[16:17], s[10:11]
	s_cbranch_execz .LBB0_369
	v_mov_b32_e32 v145, v1
	s_waitcnt vmcnt(7)
	v_pk_mul_f32 v[116:117], v[2:3], v[242:243] op_sel:[1, 1] op_sel_hi:[1, 0]
	s_nop 0
	v_pk_fma_f32 v[106:107], v[2:3], v[242:243], v[116:117] op_sel_hi:[0, 1, 1] neg_lo:[0, 0, 1] neg_hi:[0, 0, 1]
	v_pk_fma_f32 v[2:3], v[2:3], v[242:243], v[116:117] op_sel_hi:[0, 1, 1]
	v_pk_mul_f32 v[116:117], v[4:5], v[244:245] op_sel:[1, 1] op_sel_hi:[1, 0]
	v_mul_f32_e32 v2, v9, v249
	v_pk_fma_f32 v[108:109], v[4:5], v[244:245], v[116:117] op_sel_hi:[0, 1, 1] neg_lo:[0, 0, 1] neg_hi:[0, 0, 1]
	v_pk_fma_f32 v[4:5], v[4:5], v[244:245], v[116:117] op_sel_hi:[0, 1, 1]
	v_pk_mul_f32 v[116:117], v[6:7], v[246:247] op_sel:[1, 1] op_sel_hi:[1, 0]
	v_mov_b32_e32 v107, v3
	v_pk_fma_f32 v[110:111], v[6:7], v[246:247], v[116:117] op_sel_hi:[0, 1, 1] neg_lo:[0, 0, 1] neg_hi:[0, 0, 1]
	v_pk_fma_f32 v[6:7], v[6:7], v[246:247], v[116:117] op_sel_hi:[0, 1, 1]
	v_pk_fma_f32 v[112:113], v[8:9], v[248:249], v[2:3] op_sel_hi:[1, 1, 0] neg_lo:[0, 0, 1] neg_hi:[0, 0, 1]
	v_mul_f32_e32 v2, v9, v248
	v_pk_fma_f32 v[8:9], v[8:9], v[248:249], v[2:3] op_sel:[0, 1, 0] op_sel_hi:[1, 0, 0]
	v_mov_b32_e32 v109, v5
	v_mov_b32_e32 v111, v7
	v_mov_b32_e32 v113, v8
	v_mov_b64_e32 v[2:3], v[106:107]
	v_mov_b64_e32 v[4:5], v[108:109]
	v_mov_b64_e32 v[6:7], v[110:111]
	v_mov_b64_e32 v[8:9], v[112:113]

; __device__ __forceinline__ float silu_f(float x) { return x * __builtin_amdgcn_rcpf(1.0f + __builtin_amdgcn_exp2f(-x * 1.4426950408889634f)); }
; __device__ __forceinline__ void rope8(float (&v)[8], const tab_t* tp) {
;     const f32x4 t0 = *(const f32x4*)tp, t1 = *(const f32x4*)(tp + 2);
;     const float c[4] = {t0[0], t0[2], t1[0], t1[2]}, s[4] = {t0[1], t0[3], t1[1], t1[3]};
; #pragma unroll
;     for (int j = 0; j < 4; ++j) { const float a = v[2 * j], b = v[2 * j + 1]; v[2 * j] = a * c[j] - b * s[j]; v[2 * j + 1] = b * c[j] + a * s[j]; }
; }
;     __device__ __forceinline__ void operator()(const f32x4 (&acc)[2][2][4][2], const Unit& u, int wr, int wc, int fr, int fq) const {
;     ...
;                 const int row = row0 + ai * HALF + m * 16;
;                 const float r = __builtin_amdgcn_rsqf(sum_parts<8>(ssq_h + (size_t)row * 32) * (1.0f / 2048.0f) + 1e-6f);
; #pragma unroll
;                 for (int bj = 0; bj < 2; ++bj) {
;                     float v[8];
; #pragma unroll
;                     for (int e = 0; e < 4; ++e) { v[e] = acc[ai][bj][m][0][e] * r; v[4 + e] = acc[ai][bj][m][1][e] * r; }
;                     if (tab[bj] >= 0) rope8(v, TAB + (size_t)row * NTAB + tab[bj]);
;                     if (act[bj]) {
; #pragma unroll
;                         for (int e = 0; e < 8; ++e) v[e] = silu_f(v[e]);
;                     }
; #pragma unroll
;                     for (int e = 0; e < 8; ++e) v[e] *= sc[bj];
;                     if (ssq[bj]) { float s = 0.f;
; #pragma unroll
;                         for (int e = 0; e < 8; ++e) s += v[e] * v[e];
;                         s += __shfl_xor(s, 16); s += __shfl_xor(s, 32);
;                         if (fq == 0) ssq[bj][(size_t)row * sld[bj]] = s; }
;                     store8(dst[bj] + (size_t)row * ld[bj], v);
.LBB0_375:
	v_mul_lo_u32 v7, s93, v124
	v_mul_lo_u32 v109, s92, v125
	s_waitcnt lgkmcnt(0)
	v_mad_u64_u32 v[8:9], s[18:19], s92, v124, 0
	v_add3_u32 v9, v9, v109, v7
	v_lshl_add_u64 v[8:9], v[8:9], 1, v[122:123]
	v_cvt_pk_bf16_f32 v106, v106, v108
	v_cvt_pk_bf16_f32 v107, v4, v107
	v_cvt_pk_bf16_f32 v108, v3, v5
	v_cvt_pk_bf16_f32 v109, v2, v6
	global_store_dwordx4 v[8:9], v[106:109], off
	s_nop 1
	v_or_b32_e32 v106, 32, v146
	v_ashrrev_i32_e32 v107, 31, v106
	v_mad_i64_i32 v[110:111], s[18:19], v106, s1, 0
	v_mov_b32_e32 v108, v170
	s_nop 0
	v_pk_mul_f32 v[2:3], v[102:103], v[108:109] op_sel_hi:[1,0]
	v_pk_mul_f32 v[6:7], v[98:99], v[108:109] op_sel_hi:[1,0]
	v_pk_mul_f32 v[4:5], v[104:105], v[108:109] op_sel_hi:[1,0]
	v_pk_mul_f32 v[8:9], v[100:101], v[108:109] op_sel_hi:[1,0]
	v_lshl_add_u64 v[98:99], s[70:71], 0, v[110:111]
	s_and_saveexec_b64 s[18:19], s[6:7]
	s_cbranch_execz .LBB0_377
	s_waitcnt vmcnt(4)
	v_pk_mul_f32 v[104:105], v[2:3], v[218:219] op_sel:[1, 1] op_sel_hi:[1, 0]
	s_nop 0
	v_pk_fma_f32 v[110:111], v[2:3], v[218:219], v[104:105] op_sel_hi:[0, 1, 1] neg_lo:[0, 0, 1] neg_hi:[0, 0, 1]
	v_pk_fma_f32 v[2:3], v[2:3], v[218:219], v[104:105] op_sel_hi:[0, 1, 1]
	v_pk_mul_f32 v[104:105], v[4:5], v[220:221] op_sel:[1, 1] op_sel_hi:[1, 0]
	v_mul_f32_e32 v2, v9, v225
	v_pk_fma_f32 v[112:113], v[4:5], v[220:221], v[104:105] op_sel_hi:[0, 1, 1] neg_lo:[0, 0, 1] neg_hi:[0, 0, 1]
	v_pk_fma_f32 v[4:5], v[4:5], v[220:221], v[104:105] op_sel_hi:[0, 1, 1]
	v_pk_mul_f32 v[104:105], v[6:7], v[222:223] op_sel:[1, 1] op_sel_hi:[1, 0]
	v_pk_fma_f32 v[116:117], v[8:9], v[224:225], v[2:3] op_sel_hi:[1, 1, 0] neg_lo:[0, 0, 1] neg_hi:[0, 0, 1]
	v_mul_f32_e32 v2, v9, v224
	v_pk_fma_f32 v[114:115], v[6:7], v[222:223], v[104:105] op_sel_hi:[0, 1, 1] neg_lo:[0, 0, 1] neg_hi:[0, 0, 1]
	v_pk_fma_f32 v[6:7], v[6:7], v[222:223], v[104:105] op_sel_hi:[0, 1, 1]
	v_pk_fma_f32 v[8:9], v[8:9], v[224:225], v[2:3] op_sel:[0, 1, 0] op_sel_hi:[1, 0, 0]
	v_mov_b32_e32 v111, v3
	v_mov_b32_e32 v113, v5
	v_mov_b32_e32 v115, v7
	v_mov_b32_e32 v117, v8
	v_mov_b64_e32 v[2:3], v[110:111]
	v_mov_b64_e32 v[4:5], v[112:113]
	v_mov_b64_e32 v[6:7], v[114:115]
	v_mov_b64_e32 v[8:9], v[116:117]

; __device__ __forceinline__ float silu_f(float x) { return x * __builtin_amdgcn_rcpf(1.0f + __builtin_amdgcn_exp2f(-x * 1.4426950408889634f)); }
; __device__ __forceinline__ void rope8(float (&v)[8], const tab_t* tp) {
;     const f32x4 t0 = *(const f32x4*)tp, t1 = *(const f32x4*)(tp + 2);
;     const float c[4] = {t0[0], t0[2], t1[0], t1[2]}, s[4] = {t0[1], t0[3], t1[1], t1[3]};
; #pragma unroll
;     for (int j = 0; j < 4; ++j) { const float a = v[2 * j], b = v[2 * j + 1]; v[2 * j] = a * c[j] - b * s[j]; v[2 * j + 1] = b * c[j] + a * s[j]; }
; }
;     __device__ __forceinline__ void operator()(const f32x4 (&acc)[2][2][4][2], const Unit& u, int wr, int wc, int fr, int fq) const {
;     ...
;                     for (int e = 0; e < 4; ++e) { v[e] = acc[ai][bj][m][0][e] * r; v[4 + e] = acc[ai][bj][m][1][e] * r; }
;                     if (tab[bj] >= 0) rope8(v, TAB + (size_t)row * NTAB + tab[bj]);
;                     if (act[bj]) {
; #pragma unroll
;                         for (int e = 0; e < 8; ++e) v[e] = silu_f(v[e]);
;                     }
; #pragma unroll
;                     for (int e = 0; e < 8; ++e) v[e] *= sc[bj];
;                     if (ssq[bj]) { float s = 0.f;
; #pragma unroll
;                         for (int e = 0; e < 8; ++e) s += v[e] * v[e];
;                         s += __shfl_xor(s, 16); s += __shfl_xor(s, 32);
;                         if (fq == 0) ssq[bj][(size_t)row * sld[bj]] = s; }
;                     store8(dst[bj] + (size_t)row * ld[bj], v);
.LBB0_383:
	v_mul_lo_u32 v7, s91, v106
	v_mul_lo_u32 v103, s90, v107
	s_waitcnt lgkmcnt(0)
	v_mad_u64_u32 v[8:9], s[18:19], s90, v106, 0
	v_add3_u32 v9, v9, v103, v7
	v_lshl_add_u64 v[8:9], v[8:9], 1, v[148:149]
	v_cvt_pk_bf16_f32 v100, v100, v102
	v_cvt_pk_bf16_f32 v101, v4, v101
	v_cvt_pk_bf16_f32 v102, v3, v5
	v_cvt_pk_bf16_f32 v103, v2, v6
	v_mov_b32_e32 v252, 0x5400
	v_mov_b32_e32 v253, 0
	v_lshl_add_u64 v[250:251], v[252:253], 0, v[212:213]
	global_load_dwordx4 v[238:241], v[250:251], off offset:16
	global_load_dwordx4 v[234:237], v[250:251], off
	v_lshl_add_u64 v[250:251], v[252:253], 0, v[210:211]
	global_load_dwordx4 v[246:249], v[250:251], off offset:16
	global_load_dwordx4 v[242:245], v[250:251], off
	global_store_dwordx4 v[8:9], v[100:103], off
	v_mov_b32_e32 v109, v108
	v_pk_mul_f32 v[2:3], v[94:95], v[108:109]
	v_pk_mul_f32 v[6:7], v[90:91], v[108:109]
	v_pk_mul_f32 v[4:5], v[96:97], v[108:109]
	v_pk_mul_f32 v[8:9], v[92:93], v[108:109]
	s_and_saveexec_b64 s[18:19], s[10:11]
	s_cbranch_execz .LBB0_385
	v_mov_b32_e32 v145, v1
	s_waitcnt vmcnt(7)
	v_pk_mul_f32 v[100:101], v[2:3], v[226:227] op_sel:[1, 1] op_sel_hi:[1, 0]
	s_nop 0
	v_pk_fma_f32 v[90:91], v[2:3], v[226:227], v[100:101] op_sel_hi:[0, 1, 1] neg_lo:[0, 0, 1] neg_hi:[0, 0, 1]
	v_pk_fma_f32 v[2:3], v[2:3], v[226:227], v[100:101] op_sel_hi:[0, 1, 1]
	v_pk_mul_f32 v[100:101], v[4:5], v[228:229] op_sel:[1, 1] op_sel_hi:[1, 0]
	v_mul_f32_e32 v2, v9, v233
	v_pk_fma_f32 v[92:93], v[4:5], v[228:229], v[100:101] op_sel_hi:[0, 1, 1] neg_lo:[0, 0, 1] neg_hi:[0, 0, 1]
	v_pk_fma_f32 v[4:5], v[4:5], v[228:229], v[100:101] op_sel_hi:[0, 1, 1]
	v_pk_mul_f32 v[100:101], v[6:7], v[230:231] op_sel:[1, 1] op_sel_hi:[1, 0]
	v_mov_b32_e32 v91, v3
	v_pk_fma_f32 v[94:95], v[6:7], v[230:231], v[100:101] op_sel_hi:[0, 1, 1] neg_lo:[0, 0, 1] neg_hi:[0, 0, 1]
	v_pk_fma_f32 v[6:7], v[6:7], v[230:231], v[100:101] op_sel_hi:[0, 1, 1]
	v_pk_fma_f32 v[96:97], v[8:9], v[232:233], v[2:3] op_sel_hi:[1, 1, 0] neg_lo:[0, 0, 1] neg_hi:[0, 0, 1]
	v_mul_f32_e32 v2, v9, v232
	v_pk_fma_f32 v[8:9], v[8:9], v[232:233], v[2:3] op_sel:[0, 1, 0] op_sel_hi:[1, 0, 0]
	v_mov_b32_e32 v93, v5
	v_mov_b32_e32 v95, v7
	v_mov_b32_e32 v97, v8
	v_mov_b64_e32 v[2:3], v[90:91]
	v_mov_b64_e32 v[4:5], v[92:93]
	v_mov_b64_e32 v[6:7], v[94:95]
	v_mov_b64_e32 v[8:9], v[96:97]

; __device__ __forceinline__ float silu_f(float x) { return x * __builtin_amdgcn_rcpf(1.0f + __builtin_amdgcn_exp2f(-x * 1.4426950408889634f)); }
; __device__ __forceinline__ void rope8(float (&v)[8], const tab_t* tp) {
;     const f32x4 t0 = *(const f32x4*)tp, t1 = *(const f32x4*)(tp + 2);
;     const float c[4] = {t0[0], t0[2], t1[0], t1[2]}, s[4] = {t0[1], t0[3], t1[1], t1[3]};
; #pragma unroll
;     for (int j = 0; j < 4; ++j) { const float a = v[2 * j], b = v[2 * j + 1]; v[2 * j] = a * c[j] - b * s[j]; v[2 * j + 1] = b * c[j] + a * s[j]; }
; }
;     __device__ __forceinline__ void operator()(const f32x4 (&acc)[2][2][4][2], const Unit& u, int wr, int wc, int fr, int fq) const {
;     ...
;                 const int row = row0 + ai * HALF + m * 16;
;                 const float r = __builtin_amdgcn_rsqf(sum_parts<8>(ssq_h + (size_t)row * 32) * (1.0f / 2048.0f) + 1e-6f);
; #pragma unroll
;                 for (int bj = 0; bj < 2; ++bj) {
;                     float v[8];
; #pragma unroll
;                     for (int e = 0; e < 4; ++e) { v[e] = acc[ai][bj][m][0][e] * r; v[4 + e] = acc[ai][bj][m][1][e] * r; }
;                     if (tab[bj] >= 0) rope8(v, TAB + (size_t)row * NTAB + tab[bj]);
;                     if (act[bj]) {
; #pragma unroll
;                         for (int e = 0; e < 8; ++e) v[e] = silu_f(v[e]);
;                     }
; #pragma unroll
;                     for (int e = 0; e < 8; ++e) v[e] *= sc[bj];
;                     if (ssq[bj]) { float s = 0.f;
; #pragma unroll
;                         for (int e = 0; e < 8; ++e) s += v[e] * v[e];
;                         s += __shfl_xor(s, 16); s += __shfl_xor(s, 32);
;                         if (fq == 0) ssq[bj][(size_t)row * sld[bj]] = s; }
;                     store8(dst[bj] + (size_t)row * ld[bj], v);
.LBB0_391:
	v_mul_lo_u32 v7, s93, v106
	v_mul_lo_u32 v93, s92, v107
	s_waitcnt lgkmcnt(0)
	v_mad_u64_u32 v[8:9], s[18:19], s92, v106, 0
	v_add3_u32 v9, v9, v93, v7
	v_lshl_add_u64 v[8:9], v[8:9], 1, v[122:123]
	v_cvt_pk_bf16_f32 v90, v90, v92
	v_cvt_pk_bf16_f32 v91, v4, v91
	v_cvt_pk_bf16_f32 v92, v3, v5
	v_cvt_pk_bf16_f32 v93, v2, v6
	global_store_dwordx4 v[8:9], v[90:93], off
	s_nop 1
	v_or_b32_e32 v90, 48, v146
	v_ashrrev_i32_e32 v91, 31, v90
	v_mad_i64_i32 v[94:95], s[18:19], v90, s1, 0
	v_mov_b32_e32 v92, v171
	s_nop 0
	v_pk_mul_f32 v[2:3], v[86:87], v[92:93] op_sel_hi:[1,0]
	v_pk_mul_f32 v[6:7], v[82:83], v[92:93] op_sel_hi:[1,0]
	v_pk_mul_f32 v[4:5], v[88:89], v[92:93] op_sel_hi:[1,0]
	v_pk_mul_f32 v[8:9], v[84:85], v[92:93] op_sel_hi:[1,0]
	v_lshl_add_u64 v[82:83], s[70:71], 0, v[94:95]
	s_and_saveexec_b64 s[18:19], s[6:7]
	s_cbranch_execz .LBB0_393
	s_waitcnt vmcnt(4)
	v_pk_mul_f32 v[88:89], v[2:3], v[234:235] op_sel:[1, 1] op_sel_hi:[1, 0]
	s_nop 0
	v_pk_fma_f32 v[94:95], v[2:3], v[234:235], v[88:89] op_sel_hi:[0, 1, 1] neg_lo:[0, 0, 1] neg_hi:[0, 0, 1]
	v_pk_fma_f32 v[2:3], v[2:3], v[234:235], v[88:89] op_sel_hi:[0, 1, 1]
	v_pk_mul_f32 v[88:89], v[4:5], v[236:237] op_sel:[1, 1] op_sel_hi:[1, 0]
	v_mul_f32_e32 v2, v9, v241
	v_pk_fma_f32 v[96:97], v[4:5], v[236:237], v[88:89] op_sel_hi:[0, 1, 1] neg_lo:[0, 0, 1] neg_hi:[0, 0, 1]
	v_pk_fma_f32 v[4:5], v[4:5], v[236:237], v[88:89] op_sel_hi:[0, 1, 1]
	v_pk_mul_f32 v[88:89], v[6:7], v[238:239] op_sel:[1, 1] op_sel_hi:[1, 0]
	v_pk_fma_f32 v[100:101], v[8:9], v[240:241], v[2:3] op_sel_hi:[1, 1, 0] neg_lo:[0, 0, 1] neg_hi:[0, 0, 1]
	v_mul_f32_e32 v2, v9, v240
	v_pk_fma_f32 v[98:99], v[6:7], v[238:239], v[88:89] op_sel_hi:[0, 1, 1] neg_lo:[0, 0, 1] neg_hi:[0, 0, 1]
	v_pk_fma_f32 v[6:7], v[6:7], v[238:239], v[88:89] op_sel_hi:[0, 1, 1]
	v_pk_fma_f32 v[8:9], v[8:9], v[240:241], v[2:3] op_sel:[0, 1, 0] op_sel_hi:[1, 0, 0]
	v_mov_b32_e32 v95, v3
	v_mov_b32_e32 v97, v5
	v_mov_b32_e32 v99, v7
	v_mov_b32_e32 v101, v8
	v_mov_b64_e32 v[2:3], v[94:95]
	v_mov_b64_e32 v[4:5], v[96:97]
	v_mov_b64_e32 v[6:7], v[98:99]
	v_mov_b64_e32 v[8:9], v[100:101]

; __device__ __forceinline__ float silu_f(float x) { return x * __builtin_amdgcn_rcpf(1.0f + __builtin_amdgcn_exp2f(-x * 1.4426950408889634f)); }
; __device__ __forceinline__ void rope8(float (&v)[8], const tab_t* tp) {
;     const f32x4 t0 = *(const f32x4*)tp, t1 = *(const f32x4*)(tp + 2);
;     const float c[4] = {t0[0], t0[2], t1[0], t1[2]}, s[4] = {t0[1], t0[3], t1[1], t1[3]};
; #pragma unroll
;     for (int j = 0; j < 4; ++j) { const float a = v[2 * j], b = v[2 * j + 1]; v[2 * j] = a * c[j] - b * s[j]; v[2 * j + 1] = b * c[j] + a * s[j]; }
; }
;     __device__ __forceinline__ void operator()(const f32x4 (&acc)[2][2][4][2], const Unit& u, int wr, int wc, int fr, int fq) const {
;     ...
;                     for (int e = 0; e < 4; ++e) { v[e] = acc[ai][bj][m][0][e] * r; v[4 + e] = acc[ai][bj][m][1][e] * r; }
;                     if (tab[bj] >= 0) rope8(v, TAB + (size_t)row * NTAB + tab[bj]);
;                     if (act[bj]) {
; #pragma unroll
;                         for (int e = 0; e < 8; ++e) v[e] = silu_f(v[e]);
;                     }
; #pragma unroll
;                     for (int e = 0; e < 8; ++e) v[e] *= sc[bj];
;                     if (ssq[bj]) { float s = 0.f;
; #pragma unroll
;                         for (int e = 0; e < 8; ++e) s += v[e] * v[e];
;                         s += __shfl_xor(s, 16); s += __shfl_xor(s, 32);
;                         if (fq == 0) ssq[bj][(size_t)row * sld[bj]] = s; }
;                     store8(dst[bj] + (size_t)row * ld[bj], v);
.LBB0_399:
	v_mul_lo_u32 v7, s91, v90
	v_mul_lo_u32 v87, s90, v91
	s_waitcnt lgkmcnt(0)
	v_mad_u64_u32 v[8:9], s[18:19], s90, v90, 0
	v_add3_u32 v9, v9, v87, v7
	v_lshl_add_u64 v[8:9], v[8:9], 1, v[148:149]
	v_cvt_pk_bf16_f32 v84, v84, v86
	v_cvt_pk_bf16_f32 v85, v4, v85
	v_cvt_pk_bf16_f32 v86, v3, v5
	v_cvt_pk_bf16_f32 v87, v2, v6
	v_mov_b32_e32 v252, 0xe000
	v_mov_b32_e32 v253, 0
	v_lshl_add_u64 v[250:251], v[252:253], 0, v[212:213]
	global_load_dwordx4 v[222:225], v[250:251], off offset:16
	global_load_dwordx4 v[218:221], v[250:251], off
	v_lshl_add_u64 v[250:251], v[252:253], 0, v[210:211]
	global_load_dwordx4 v[230:233], v[250:251], off offset:16
	global_load_dwordx4 v[226:229], v[250:251], off
	global_store_dwordx4 v[8:9], v[84:87], off
	v_mov_b32_e32 v93, v92
	v_pk_mul_f32 v[2:3], v[78:79], v[92:93]
	v_pk_mul_f32 v[6:7], v[74:75], v[92:93]
	v_pk_mul_f32 v[4:5], v[80:81], v[92:93]
	v_pk_mul_f32 v[8:9], v[76:77], v[92:93]
	s_and_saveexec_b64 s[18:19], s[10:11]
	s_cbranch_execz .LBB0_401
	v_mov_b32_e32 v145, v1
	s_waitcnt vmcnt(7)
	v_pk_mul_f32 v[84:85], v[2:3], v[242:243] op_sel:[1, 1] op_sel_hi:[1, 0]
	s_nop 0
	v_pk_fma_f32 v[74:75], v[2:3], v[242:243], v[84:85] op_sel_hi:[0, 1, 1] neg_lo:[0, 0, 1] neg_hi:[0, 0, 1]
	v_pk_fma_f32 v[2:3], v[2:3], v[242:243], v[84:85] op_sel_hi:[0, 1, 1]
	v_pk_mul_f32 v[84:85], v[4:5], v[244:245] op_sel:[1, 1] op_sel_hi:[1, 0]
	v_mul_f32_e32 v2, v9, v249
	v_pk_fma_f32 v[76:77], v[4:5], v[244:245], v[84:85] op_sel_hi:[0, 1, 1] neg_lo:[0, 0, 1] neg_hi:[0, 0, 1]
	v_pk_fma_f32 v[4:5], v[4:5], v[244:245], v[84:85] op_sel_hi:[0, 1, 1]
	v_pk_mul_f32 v[84:85], v[6:7], v[246:247] op_sel:[1, 1] op_sel_hi:[1, 0]
	v_mov_b32_e32 v75, v3
	v_pk_fma_f32 v[78:79], v[6:7], v[246:247], v[84:85] op_sel_hi:[0, 1, 1] neg_lo:[0, 0, 1] neg_hi:[0, 0, 1]
	v_pk_fma_f32 v[6:7], v[6:7], v[246:247], v[84:85] op_sel_hi:[0, 1, 1]
	v_pk_fma_f32 v[80:81], v[8:9], v[248:249], v[2:3] op_sel_hi:[1, 1, 0] neg_lo:[0, 0, 1] neg_hi:[0, 0, 1]
	v_mul_f32_e32 v2, v9, v248
	v_pk_fma_f32 v[8:9], v[8:9], v[248:249], v[2:3] op_sel:[0, 1, 0] op_sel_hi:[1, 0, 0]
	v_mov_b32_e32 v77, v5
	v_mov_b32_e32 v79, v7
	v_mov_b32_e32 v81, v8
	v_mov_b64_e32 v[2:3], v[74:75]
	v_mov_b64_e32 v[4:5], v[76:77]
	v_mov_b64_e32 v[6:7], v[78:79]
	v_mov_b64_e32 v[8:9], v[80:81]

; __device__ __forceinline__ float silu_f(float x) { return x * __builtin_amdgcn_rcpf(1.0f + __builtin_amdgcn_exp2f(-x * 1.4426950408889634f)); }
; __device__ __forceinline__ void rope8(float (&v)[8], const tab_t* tp) {
;     const f32x4 t0 = *(const f32x4*)tp, t1 = *(const f32x4*)(tp + 2);
;     const float c[4] = {t0[0], t0[2], t1[0], t1[2]}, s[4] = {t0[1], t0[3], t1[1], t1[3]};
; #pragma unroll
;     for (int j = 0; j < 4; ++j) { const float a = v[2 * j], b = v[2 * j + 1]; v[2 * j] = a * c[j] - b * s[j]; v[2 * j + 1] = b * c[j] + a * s[j]; }
; }
;     __device__ __forceinline__ void operator()(const f32x4 (&acc)[2][2][4][2], const Unit& u, int wr, int wc, int fr, int fq) const {
;     ...
;                 const int row = row0 + ai * HALF + m * 16;
;                 const float r = __builtin_amdgcn_rsqf(sum_parts<8>(ssq_h + (size_t)row * 32) * (1.0f / 2048.0f) + 1e-6f);
; #pragma unroll
;                 for (int bj = 0; bj < 2; ++bj) {
;                     float v[8];
; #pragma unroll
;                     for (int e = 0; e < 4; ++e) { v[e] = acc[ai][bj][m][0][e] * r; v[4 + e] = acc[ai][bj][m][1][e] * r; }
;                     if (tab[bj] >= 0) rope8(v, TAB + (size_t)row * NTAB + tab[bj]);
;                     if (act[bj]) {
; #pragma unroll
;                         for (int e = 0; e < 8; ++e) v[e] = silu_f(v[e]);
;                     }
; #pragma unroll
;                     for (int e = 0; e < 8; ++e) v[e] *= sc[bj];
;                     if (ssq[bj]) { float s = 0.f;
; #pragma unroll
;                         for (int e = 0; e < 8; ++e) s += v[e] * v[e];
;                         s += __shfl_xor(s, 16); s += __shfl_xor(s, 32);
;                         if (fq == 0) ssq[bj][(size_t)row * sld[bj]] = s; }
;                     store8(dst[bj] + (size_t)row * ld[bj], v);
.LBB0_407:
	v_mul_lo_u32 v7, s93, v90
	v_mul_lo_u32 v77, s92, v91
	s_waitcnt lgkmcnt(0)
	v_mad_u64_u32 v[8:9], s[18:19], s92, v90, 0
	v_add3_u32 v9, v9, v77, v7
	v_lshl_add_u64 v[8:9], v[8:9], 1, v[122:123]
	v_cvt_pk_bf16_f32 v74, v74, v76
	v_cvt_pk_bf16_f32 v75, v4, v75
	v_cvt_pk_bf16_f32 v76, v3, v5
	v_cvt_pk_bf16_f32 v77, v2, v6
	global_store_dwordx4 v[8:9], v[74:77], off
	s_nop 1
	v_add_u32_e32 v74, 0x80, v146
	v_ashrrev_i32_e32 v75, 31, v74
	v_mad_i64_i32 v[78:79], s[18:19], v74, s1, 0
	v_mov_b32_e32 v76, v172
	s_nop 0
	v_pk_mul_f32 v[2:3], v[70:71], v[76:77] op_sel_hi:[1,0]
	v_pk_mul_f32 v[6:7], v[66:67], v[76:77] op_sel_hi:[1,0]
	v_pk_mul_f32 v[4:5], v[72:73], v[76:77] op_sel_hi:[1,0]
	v_pk_mul_f32 v[8:9], v[68:69], v[76:77] op_sel_hi:[1,0]
	v_lshl_add_u64 v[66:67], s[70:71], 0, v[78:79]
	s_and_saveexec_b64 s[18:19], s[6:7]
	s_cbranch_execz .LBB0_409
	s_waitcnt vmcnt(4)
	v_pk_mul_f32 v[72:73], v[2:3], v[218:219] op_sel:[1, 1] op_sel_hi:[1, 0]
	s_nop 0
	v_pk_fma_f32 v[78:79], v[2:3], v[218:219], v[72:73] op_sel_hi:[0, 1, 1] neg_lo:[0, 0, 1] neg_hi:[0, 0, 1]
	v_pk_fma_f32 v[2:3], v[2:3], v[218:219], v[72:73] op_sel_hi:[0, 1, 1]
	v_pk_mul_f32 v[72:73], v[4:5], v[220:221] op_sel:[1, 1] op_sel_hi:[1, 0]
	v_mul_f32_e32 v2, v9, v225
	v_pk_fma_f32 v[80:81], v[4:5], v[220:221], v[72:73] op_sel_hi:[0, 1, 1] neg_lo:[0, 0, 1] neg_hi:[0, 0, 1]
	v_pk_fma_f32 v[4:5], v[4:5], v[220:221], v[72:73] op_sel_hi:[0, 1, 1]
	v_pk_mul_f32 v[72:73], v[6:7], v[222:223] op_sel:[1, 1] op_sel_hi:[1, 0]
	v_pk_fma_f32 v[84:85], v[8:9], v[224:225], v[2:3] op_sel_hi:[1, 1, 0] neg_lo:[0, 0, 1] neg_hi:[0, 0, 1]
	v_mul_f32_e32 v2, v9, v224
	v_pk_fma_f32 v[82:83], v[6:7], v[222:223], v[72:73] op_sel_hi:[0, 1, 1] neg_lo:[0, 0, 1] neg_hi:[0, 0, 1]
	v_pk_fma_f32 v[6:7], v[6:7], v[222:223], v[72:73] op_sel_hi:[0, 1, 1]
	v_pk_fma_f32 v[8:9], v[8:9], v[224:225], v[2:3] op_sel:[0, 1, 0] op_sel_hi:[1, 0, 0]
	v_mov_b32_e32 v79, v3
	v_mov_b32_e32 v81, v5
	v_mov_b32_e32 v83, v7
	v_mov_b32_e32 v85, v8
	v_mov_b64_e32 v[2:3], v[78:79]
	v_mov_b64_e32 v[4:5], v[80:81]
	v_mov_b64_e32 v[6:7], v[82:83]
	v_mov_b64_e32 v[8:9], v[84:85]

; __device__ __forceinline__ float silu_f(float x) { return x * __builtin_amdgcn_rcpf(1.0f + __builtin_amdgcn_exp2f(-x * 1.4426950408889634f)); }
; __device__ __forceinline__ void rope8(float (&v)[8], const tab_t* tp) {
;     const f32x4 t0 = *(const f32x4*)tp, t1 = *(const f32x4*)(tp + 2);
;     const float c[4] = {t0[0], t0[2], t1[0], t1[2]}, s[4] = {t0[1], t0[3], t1[1], t1[3]};
; #pragma unroll
;     for (int j = 0; j < 4; ++j) { const float a = v[2 * j], b = v[2 * j + 1]; v[2 * j] = a * c[j] - b * s[j]; v[2 * j + 1] = b * c[j] + a * s[j]; }
; }
;     __device__ __forceinline__ void operator()(const f32x4 (&acc)[2][2][4][2], const Unit& u, int wr, int wc, int fr, int fq) const {
;     ...
;                     for (int e = 0; e < 4; ++e) { v[e] = acc[ai][bj][m][0][e] * r; v[4 + e] = acc[ai][bj][m][1][e] * r; }
;                     if (tab[bj] >= 0) rope8(v, TAB + (size_t)row * NTAB + tab[bj]);
;                     if (act[bj]) {
; #pragma unroll
;                         for (int e = 0; e < 8; ++e) v[e] = silu_f(v[e]);
;                     }
; #pragma unroll
;                     for (int e = 0; e < 8; ++e) v[e] *= sc[bj];
;                     if (ssq[bj]) { float s = 0.f;
; #pragma unroll
;                         for (int e = 0; e < 8; ++e) s += v[e] * v[e];
;                         s += __shfl_xor(s, 16); s += __shfl_xor(s, 32);
;                         if (fq == 0) ssq[bj][(size_t)row * sld[bj]] = s; }
;                     store8(dst[bj] + (size_t)row * ld[bj], v);
.LBB0_415:
	v_mul_lo_u32 v7, s91, v74
	v_mul_lo_u32 v71, s90, v75
	s_waitcnt lgkmcnt(0)
	v_mad_u64_u32 v[8:9], s[18:19], s90, v74, 0
	v_add3_u32 v9, v9, v71, v7
	v_lshl_add_u64 v[8:9], v[8:9], 1, v[148:149]
	v_cvt_pk_bf16_f32 v68, v68, v70
	v_cvt_pk_bf16_f32 v69, v4, v69
	v_cvt_pk_bf16_f32 v70, v3, v5
	v_cvt_pk_bf16_f32 v71, v2, v6
	v_mov_b32_e32 v252, 0xfc00
	v_mov_b32_e32 v253, 0
	v_lshl_add_u64 v[250:251], v[252:253], 0, v[212:213]
	global_load_dwordx4 v[238:241], v[250:251], off offset:16
	global_load_dwordx4 v[234:237], v[250:251], off
	v_lshl_add_u64 v[250:251], v[252:253], 0, v[210:211]
	global_load_dwordx4 v[246:249], v[250:251], off offset:16
	global_load_dwordx4 v[242:245], v[250:251], off
	global_store_dwordx4 v[8:9], v[68:71], off
	v_mov_b32_e32 v77, v76
	v_pk_mul_f32 v[2:3], v[62:63], v[76:77]
	v_pk_mul_f32 v[6:7], v[58:59], v[76:77]
	v_pk_mul_f32 v[4:5], v[64:65], v[76:77]
	v_pk_mul_f32 v[8:9], v[60:61], v[76:77]
	s_and_saveexec_b64 s[18:19], s[10:11]
	s_cbranch_execz .LBB0_417
	v_mov_b32_e32 v145, v1
	s_waitcnt vmcnt(7)
	v_pk_mul_f32 v[68:69], v[2:3], v[226:227] op_sel:[1, 1] op_sel_hi:[1, 0]
	s_nop 0
	v_pk_fma_f32 v[58:59], v[2:3], v[226:227], v[68:69] op_sel_hi:[0, 1, 1] neg_lo:[0, 0, 1] neg_hi:[0, 0, 1]
	v_pk_fma_f32 v[2:3], v[2:3], v[226:227], v[68:69] op_sel_hi:[0, 1, 1]
	v_pk_mul_f32 v[68:69], v[4:5], v[228:229] op_sel:[1, 1] op_sel_hi:[1, 0]
	v_mul_f32_e32 v2, v9, v233
	v_pk_fma_f32 v[60:61], v[4:5], v[228:229], v[68:69] op_sel_hi:[0, 1, 1] neg_lo:[0, 0, 1] neg_hi:[0, 0, 1]
	v_pk_fma_f32 v[4:5], v[4:5], v[228:229], v[68:69] op_sel_hi:[0, 1, 1]
	v_pk_mul_f32 v[68:69], v[6:7], v[230:231] op_sel:[1, 1] op_sel_hi:[1, 0]
	v_mov_b32_e32 v59, v3
	v_pk_fma_f32 v[62:63], v[6:7], v[230:231], v[68:69] op_sel_hi:[0, 1, 1] neg_lo:[0, 0, 1] neg_hi:[0, 0, 1]
	v_pk_fma_f32 v[6:7], v[6:7], v[230:231], v[68:69] op_sel_hi:[0, 1, 1]
	v_pk_fma_f32 v[64:65], v[8:9], v[232:233], v[2:3] op_sel_hi:[1, 1, 0] neg_lo:[0, 0, 1] neg_hi:[0, 0, 1]
	v_mul_f32_e32 v2, v9, v232
	v_pk_fma_f32 v[8:9], v[8:9], v[232:233], v[2:3] op_sel:[0, 1, 0] op_sel_hi:[1, 0, 0]
	v_mov_b32_e32 v61, v5
	v_mov_b32_e32 v63, v7
	v_mov_b32_e32 v65, v8
	v_mov_b64_e32 v[2:3], v[58:59]
	v_mov_b64_e32 v[4:5], v[60:61]
	v_mov_b64_e32 v[6:7], v[62:63]
	v_mov_b64_e32 v[8:9], v[64:65]

; __device__ __forceinline__ float silu_f(float x) { return x * __builtin_amdgcn_rcpf(1.0f + __builtin_amdgcn_exp2f(-x * 1.4426950408889634f)); }
; __device__ __forceinline__ void rope8(float (&v)[8], const tab_t* tp) {
;     const f32x4 t0 = *(const f32x4*)tp, t1 = *(const f32x4*)(tp + 2);
;     const float c[4] = {t0[0], t0[2], t1[0], t1[2]}, s[4] = {t0[1], t0[3], t1[1], t1[3]};
; #pragma unroll
;     for (int j = 0; j < 4; ++j) { const float a = v[2 * j], b = v[2 * j + 1]; v[2 * j] = a * c[j] - b * s[j]; v[2 * j + 1] = b * c[j] + a * s[j]; }
; }
;     __device__ __forceinline__ void operator()(const f32x4 (&acc)[2][2][4][2], const Unit& u, int wr, int wc, int fr, int fq) const {
;     ...
;                 const int row = row0 + ai * HALF + m * 16;
;                 const float r = __builtin_amdgcn_rsqf(sum_parts<8>(ssq_h + (size_t)row * 32) * (1.0f / 2048.0f) + 1e-6f);
; #pragma unroll
;                 for (int bj = 0; bj < 2; ++bj) {
;                     float v[8];
; #pragma unroll
;                     for (int e = 0; e < 4; ++e) { v[e] = acc[ai][bj][m][0][e] * r; v[4 + e] = acc[ai][bj][m][1][e] * r; }
;                     if (tab[bj] >= 0) rope8(v, TAB + (size_t)row * NTAB + tab[bj]);
;                     if (act[bj]) {
; #pragma unroll
;                         for (int e = 0; e < 8; ++e) v[e] = silu_f(v[e]);
;                     }
; #pragma unroll
;                     for (int e = 0; e < 8; ++e) v[e] *= sc[bj];
;                     if (ssq[bj]) { float s = 0.f;
; #pragma unroll
;                         for (int e = 0; e < 8; ++e) s += v[e] * v[e];
;                         s += __shfl_xor(s, 16); s += __shfl_xor(s, 32);
;                         if (fq == 0) ssq[bj][(size_t)row * sld[bj]] = s; }
;                     store8(dst[bj] + (size_t)row * ld[bj], v);
.LBB0_423:
	v_mul_lo_u32 v7, s93, v74
	v_mul_lo_u32 v61, s92, v75
	s_waitcnt lgkmcnt(0)
	v_mad_u64_u32 v[8:9], s[18:19], s92, v74, 0
	v_add3_u32 v9, v9, v61, v7
	v_lshl_add_u64 v[8:9], v[8:9], 1, v[122:123]
	v_cvt_pk_bf16_f32 v58, v58, v60
	v_cvt_pk_bf16_f32 v59, v4, v59
	v_cvt_pk_bf16_f32 v60, v3, v5
	v_cvt_pk_bf16_f32 v61, v2, v6
	global_store_dwordx4 v[8:9], v[58:61], off
	s_nop 1
	v_add_u32_e32 v58, 0x90, v146
	v_ashrrev_i32_e32 v59, 31, v58
	v_mad_i64_i32 v[62:63], s[18:19], v58, s1, 0
	v_mov_b32_e32 v60, v173
	s_nop 0
	v_pk_mul_f32 v[2:3], v[54:55], v[60:61] op_sel_hi:[1,0]
	v_pk_mul_f32 v[6:7], v[50:51], v[60:61] op_sel_hi:[1,0]
	v_pk_mul_f32 v[4:5], v[56:57], v[60:61] op_sel_hi:[1,0]
	v_pk_mul_f32 v[8:9], v[52:53], v[60:61] op_sel_hi:[1,0]
	v_lshl_add_u64 v[50:51], s[70:71], 0, v[62:63]
	s_and_saveexec_b64 s[18:19], s[6:7]
	s_cbranch_execz .LBB0_425
	s_waitcnt vmcnt(4)
	v_pk_mul_f32 v[56:57], v[2:3], v[234:235] op_sel:[1, 1] op_sel_hi:[1, 0]
	s_nop 0
	v_pk_fma_f32 v[62:63], v[2:3], v[234:235], v[56:57] op_sel_hi:[0, 1, 1] neg_lo:[0, 0, 1] neg_hi:[0, 0, 1]
	v_pk_fma_f32 v[2:3], v[2:3], v[234:235], v[56:57] op_sel_hi:[0, 1, 1]
	v_pk_mul_f32 v[56:57], v[4:5], v[236:237] op_sel:[1, 1] op_sel_hi:[1, 0]
	v_mul_f32_e32 v2, v9, v241
	v_pk_fma_f32 v[64:65], v[4:5], v[236:237], v[56:57] op_sel_hi:[0, 1, 1] neg_lo:[0, 0, 1] neg_hi:[0, 0, 1]
	v_pk_fma_f32 v[4:5], v[4:5], v[236:237], v[56:57] op_sel_hi:[0, 1, 1]
	v_pk_mul_f32 v[56:57], v[6:7], v[238:239] op_sel:[1, 1] op_sel_hi:[1, 0]
	v_pk_fma_f32 v[68:69], v[8:9], v[240:241], v[2:3] op_sel_hi:[1, 1, 0] neg_lo:[0, 0, 1] neg_hi:[0, 0, 1]
	v_mul_f32_e32 v2, v9, v240
	v_pk_fma_f32 v[66:67], v[6:7], v[238:239], v[56:57] op_sel_hi:[0, 1, 1] neg_lo:[0, 0, 1] neg_hi:[0, 0, 1]
	v_pk_fma_f32 v[6:7], v[6:7], v[238:239], v[56:57] op_sel_hi:[0, 1, 1]
	v_pk_fma_f32 v[8:9], v[8:9], v[240:241], v[2:3] op_sel:[0, 1, 0] op_sel_hi:[1, 0, 0]
	v_mov_b32_e32 v63, v3
	v_mov_b32_e32 v65, v5
	v_mov_b32_e32 v67, v7
	v_mov_b32_e32 v69, v8
	v_mov_b64_e32 v[2:3], v[62:63]
	v_mov_b64_e32 v[4:5], v[64:65]
	v_mov_b64_e32 v[6:7], v[66:67]
	v_mov_b64_e32 v[8:9], v[68:69]

; __device__ __forceinline__ float silu_f(float x) { return x * __builtin_amdgcn_rcpf(1.0f + __builtin_amdgcn_exp2f(-x * 1.4426950408889634f)); }
; __device__ __forceinline__ void rope8(float (&v)[8], const tab_t* tp) {
;     const f32x4 t0 = *(const f32x4*)tp, t1 = *(const f32x4*)(tp + 2);
;     const float c[4] = {t0[0], t0[2], t1[0], t1[2]}, s[4] = {t0[1], t0[3], t1[1], t1[3]};
; #pragma unroll
;     for (int j = 0; j < 4; ++j) { const float a = v[2 * j], b = v[2 * j + 1]; v[2 * j] = a * c[j] - b * s[j]; v[2 * j + 1] = b * c[j] + a * s[j]; }
; }
;     __device__ __forceinline__ void operator()(const f32x4 (&acc)[2][2][4][2], const Unit& u, int wr, int wc, int fr, int fq) const {
;     ...
;                 for (int bj = 0; bj < 2; ++bj) {
;                     float v[8];
; #pragma unroll
;                     for (int e = 0; e < 4; ++e) { v[e] = acc[ai][bj][m][0][e] * r; v[4 + e] = acc[ai][bj][m][1][e] * r; }
;                     if (tab[bj] >= 0) rope8(v, TAB + (size_t)row * NTAB + tab[bj]);
;                     if (act[bj]) {
; #pragma unroll
;                         for (int e = 0; e < 8; ++e) v[e] = silu_f(v[e]);
;                     }
; #pragma unroll
;                     for (int e = 0; e < 8; ++e) v[e] *= sc[bj];
;                     if (ssq[bj]) { float s = 0.f;
; #pragma unroll
;                         for (int e = 0; e < 8; ++e) s += v[e] * v[e];
;                         s += __shfl_xor(s, 16); s += __shfl_xor(s, 32);
;                         if (fq == 0) ssq[bj][(size_t)row * sld[bj]] = s; }
;                     store8(dst[bj] + (size_t)row * ld[bj], v);
.LBB0_431:
	v_mul_lo_u32 v7, s91, v58
	v_mul_lo_u32 v55, s90, v59
	s_waitcnt lgkmcnt(0)
	v_mad_u64_u32 v[8:9], s[18:19], s90, v58, 0
	v_add3_u32 v9, v9, v55, v7
	v_lshl_add_u64 v[8:9], v[8:9], 1, v[148:149]
	v_cvt_pk_bf16_f32 v52, v52, v54
	v_cvt_pk_bf16_f32 v53, v4, v53
	v_cvt_pk_bf16_f32 v54, v3, v5
	v_cvt_pk_bf16_f32 v55, v2, v6
	v_mov_b32_e32 v252, 0x11800
	v_mov_b32_e32 v253, 0
	v_lshl_add_u64 v[250:251], v[252:253], 0, v[212:213]
	global_load_dwordx4 v[222:225], v[250:251], off offset:16
	global_load_dwordx4 v[218:221], v[250:251], off
	v_lshl_add_u64 v[250:251], v[252:253], 0, v[210:211]
	global_load_dwordx4 v[230:233], v[250:251], off offset:16
	global_load_dwordx4 v[226:229], v[250:251], off
	global_store_dwordx4 v[8:9], v[52:55], off
	v_mov_b32_e32 v61, v60
	v_pk_mul_f32 v[2:3], v[46:47], v[60:61]
	v_pk_mul_f32 v[6:7], v[42:43], v[60:61]
	v_pk_mul_f32 v[4:5], v[48:49], v[60:61]
	v_pk_mul_f32 v[8:9], v[44:45], v[60:61]
	s_and_saveexec_b64 s[18:19], s[10:11]
	s_cbranch_execz .LBB0_433
	v_mov_b32_e32 v145, v1
	s_waitcnt vmcnt(7)
	v_pk_mul_f32 v[52:53], v[2:3], v[242:243] op_sel:[1, 1] op_sel_hi:[1, 0]
	s_nop 0
	v_pk_fma_f32 v[42:43], v[2:3], v[242:243], v[52:53] op_sel_hi:[0, 1, 1] neg_lo:[0, 0, 1] neg_hi:[0, 0, 1]
	v_pk_fma_f32 v[2:3], v[2:3], v[242:243], v[52:53] op_sel_hi:[0, 1, 1]
	v_pk_mul_f32 v[52:53], v[4:5], v[244:245] op_sel:[1, 1] op_sel_hi:[1, 0]
	v_mul_f32_e32 v2, v9, v249
	v_pk_fma_f32 v[44:45], v[4:5], v[244:245], v[52:53] op_sel_hi:[0, 1, 1] neg_lo:[0, 0, 1] neg_hi:[0, 0, 1]
	v_pk_fma_f32 v[4:5], v[4:5], v[244:245], v[52:53] op_sel_hi:[0, 1, 1]
	v_pk_mul_f32 v[52:53], v[6:7], v[246:247] op_sel:[1, 1] op_sel_hi:[1, 0]
	v_mov_b32_e32 v43, v3
	v_pk_fma_f32 v[46:47], v[6:7], v[246:247], v[52:53] op_sel_hi:[0, 1, 1] neg_lo:[0, 0, 1] neg_hi:[0, 0, 1]
	v_pk_fma_f32 v[6:7], v[6:7], v[246:247], v[52:53] op_sel_hi:[0, 1, 1]
	v_pk_fma_f32 v[48:49], v[8:9], v[248:249], v[2:3] op_sel_hi:[1, 1, 0] neg_lo:[0, 0, 1] neg_hi:[0, 0, 1]
	v_mul_f32_e32 v2, v9, v248
	v_pk_fma_f32 v[8:9], v[8:9], v[248:249], v[2:3] op_sel:[0, 1, 0] op_sel_hi:[1, 0, 0]
	v_mov_b32_e32 v45, v5
	v_mov_b32_e32 v47, v7
	v_mov_b32_e32 v49, v8
	v_mov_b64_e32 v[2:3], v[42:43]
	v_mov_b64_e32 v[4:5], v[44:45]
	v_mov_b64_e32 v[6:7], v[46:47]
	v_mov_b64_e32 v[8:9], v[48:49]

; __device__ __forceinline__ float silu_f(float x) { return x * __builtin_amdgcn_rcpf(1.0f + __builtin_amdgcn_exp2f(-x * 1.4426950408889634f)); }
; __device__ __forceinline__ void rope8(float (&v)[8], const tab_t* tp) {
;     const f32x4 t0 = *(const f32x4*)tp, t1 = *(const f32x4*)(tp + 2);
;     const float c[4] = {t0[0], t0[2], t1[0], t1[2]}, s[4] = {t0[1], t0[3], t1[1], t1[3]};
; #pragma unroll
;     for (int j = 0; j < 4; ++j) { const float a = v[2 * j], b = v[2 * j + 1]; v[2 * j] = a * c[j] - b * s[j]; v[2 * j + 1] = b * c[j] + a * s[j]; }
; }
;     __device__ __forceinline__ void operator()(const f32x4 (&acc)[2][2][4][2], const Unit& u, int wr, int wc, int fr, int fq) const {
;     ...
;                 const int row = row0 + ai * HALF + m * 16;
;                 const float r = __builtin_amdgcn_rsqf(sum_parts<8>(ssq_h + (size_t)row * 32) * (1.0f / 2048.0f) + 1e-6f);
; #pragma unroll
;                 for (int bj = 0; bj < 2; ++bj) {
;                     float v[8];
; #pragma unroll
;                     for (int e = 0; e < 4; ++e) { v[e] = acc[ai][bj][m][0][e] * r; v[4 + e] = acc[ai][bj][m][1][e] * r; }
;                     if (tab[bj] >= 0) rope8(v, TAB + (size_t)row * NTAB + tab[bj]);
;                     if (act[bj]) {
; #pragma unroll
;                         for (int e = 0; e < 8; ++e) v[e] = silu_f(v[e]);
;                     }
; #pragma unroll
;                     for (int e = 0; e < 8; ++e) v[e] *= sc[bj];
;                     if (ssq[bj]) { float s = 0.f;
; #pragma unroll
;                         for (int e = 0; e < 8; ++e) s += v[e] * v[e];
;                         s += __shfl_xor(s, 16); s += __shfl_xor(s, 32);
;                         if (fq == 0) ssq[bj][(size_t)row * sld[bj]] = s; }
;                     store8(dst[bj] + (size_t)row * ld[bj], v);
.LBB0_439:
	v_mul_lo_u32 v7, s93, v58
	v_mul_lo_u32 v45, s92, v59
	s_waitcnt lgkmcnt(0)
	v_mad_u64_u32 v[8:9], s[18:19], s92, v58, 0
	v_add3_u32 v9, v9, v45, v7
	v_lshl_add_u64 v[8:9], v[8:9], 1, v[122:123]
	v_cvt_pk_bf16_f32 v42, v42, v44
	v_cvt_pk_bf16_f32 v43, v4, v43
	v_cvt_pk_bf16_f32 v44, v3, v5
	v_cvt_pk_bf16_f32 v45, v2, v6
	global_store_dwordx4 v[8:9], v[42:45], off
	s_nop 1
	v_add_u32_e32 v42, 0xa0, v146
	v_ashrrev_i32_e32 v43, 31, v42
	v_mad_i64_i32 v[46:47], s[18:19], v42, s1, 0
	v_mov_b32_e32 v44, v174
	s_nop 0
	v_pk_mul_f32 v[2:3], v[38:39], v[44:45] op_sel_hi:[1,0]
	v_pk_mul_f32 v[6:7], v[34:35], v[44:45] op_sel_hi:[1,0]
	v_pk_mul_f32 v[4:5], v[40:41], v[44:45] op_sel_hi:[1,0]
	v_pk_mul_f32 v[8:9], v[36:37], v[44:45] op_sel_hi:[1,0]
	v_lshl_add_u64 v[34:35], s[70:71], 0, v[46:47]
	s_and_saveexec_b64 s[18:19], s[6:7]
	s_cbranch_execz .LBB0_441
	s_waitcnt vmcnt(4)
	v_pk_mul_f32 v[40:41], v[2:3], v[218:219] op_sel:[1, 1] op_sel_hi:[1, 0]
	s_nop 0
	v_pk_fma_f32 v[46:47], v[2:3], v[218:219], v[40:41] op_sel_hi:[0, 1, 1] neg_lo:[0, 0, 1] neg_hi:[0, 0, 1]
	v_pk_fma_f32 v[2:3], v[2:3], v[218:219], v[40:41] op_sel_hi:[0, 1, 1]
	v_pk_mul_f32 v[40:41], v[4:5], v[220:221] op_sel:[1, 1] op_sel_hi:[1, 0]
	v_mul_f32_e32 v2, v9, v225
	v_pk_fma_f32 v[48:49], v[4:5], v[220:221], v[40:41] op_sel_hi:[0, 1, 1] neg_lo:[0, 0, 1] neg_hi:[0, 0, 1]
	v_pk_fma_f32 v[4:5], v[4:5], v[220:221], v[40:41] op_sel_hi:[0, 1, 1]
	v_pk_mul_f32 v[40:41], v[6:7], v[222:223] op_sel:[1, 1] op_sel_hi:[1, 0]
	v_pk_fma_f32 v[52:53], v[8:9], v[224:225], v[2:3] op_sel_hi:[1, 1, 0] neg_lo:[0, 0, 1] neg_hi:[0, 0, 1]
	v_mul_f32_e32 v2, v9, v224
	v_pk_fma_f32 v[50:51], v[6:7], v[222:223], v[40:41] op_sel_hi:[0, 1, 1] neg_lo:[0, 0, 1] neg_hi:[0, 0, 1]
	v_pk_fma_f32 v[6:7], v[6:7], v[222:223], v[40:41] op_sel_hi:[0, 1, 1]
	v_pk_fma_f32 v[8:9], v[8:9], v[224:225], v[2:3] op_sel:[0, 1, 0] op_sel_hi:[1, 0, 0]
	v_mov_b32_e32 v47, v3
	v_mov_b32_e32 v49, v5
	v_mov_b32_e32 v51, v7
	v_mov_b32_e32 v53, v8
	v_mov_b64_e32 v[2:3], v[46:47]
	v_mov_b64_e32 v[4:5], v[48:49]
	v_mov_b64_e32 v[6:7], v[50:51]
	v_mov_b64_e32 v[8:9], v[52:53]

; __device__ __forceinline__ float silu_f(float x) { return x * __builtin_amdgcn_rcpf(1.0f + __builtin_amdgcn_exp2f(-x * 1.4426950408889634f)); }
; __device__ __forceinline__ void rope8(float (&v)[8], const tab_t* tp) {
;     const f32x4 t0 = *(const f32x4*)tp, t1 = *(const f32x4*)(tp + 2);
;     const float c[4] = {t0[0], t0[2], t1[0], t1[2]}, s[4] = {t0[1], t0[3], t1[1], t1[3]};
; #pragma unroll
;     for (int j = 0; j < 4; ++j) { const float a = v[2 * j], b = v[2 * j + 1]; v[2 * j] = a * c[j] - b * s[j]; v[2 * j + 1] = b * c[j] + a * s[j]; }
; }
;     __device__ __forceinline__ void operator()(const f32x4 (&acc)[2][2][4][2], const Unit& u, int wr, int wc, int fr, int fq) const {
;     ...
;                 for (int bj = 0; bj < 2; ++bj) {
;                     float v[8];
; #pragma unroll
;                     for (int e = 0; e < 4; ++e) { v[e] = acc[ai][bj][m][0][e] * r; v[4 + e] = acc[ai][bj][m][1][e] * r; }
;                     if (tab[bj] >= 0) rope8(v, TAB + (size_t)row * NTAB + tab[bj]);
;                     if (act[bj]) {
; #pragma unroll
;                         for (int e = 0; e < 8; ++e) v[e] = silu_f(v[e]);
;                     }
; #pragma unroll
;                     for (int e = 0; e < 8; ++e) v[e] *= sc[bj];
;                     if (ssq[bj]) { float s = 0.f;
; #pragma unroll
;                         for (int e = 0; e < 8; ++e) s += v[e] * v[e];
;                         s += __shfl_xor(s, 16); s += __shfl_xor(s, 32);
;                         if (fq == 0) ssq[bj][(size_t)row * sld[bj]] = s; }
;                     store8(dst[bj] + (size_t)row * ld[bj], v);
.LBB0_447:
	v_mul_lo_u32 v7, s91, v42
	v_mul_lo_u32 v39, s90, v43
	s_waitcnt lgkmcnt(0)
	v_mad_u64_u32 v[8:9], s[18:19], s90, v42, 0
	v_add3_u32 v9, v9, v39, v7
	v_lshl_add_u64 v[8:9], v[8:9], 1, v[148:149]
	v_cvt_pk_bf16_f32 v36, v36, v38
	v_cvt_pk_bf16_f32 v37, v4, v37
	v_cvt_pk_bf16_f32 v38, v3, v5
	v_cvt_pk_bf16_f32 v39, v2, v6
	v_mov_b32_e32 v252, 0x13400
	v_mov_b32_e32 v253, 0
	v_lshl_add_u64 v[250:251], v[252:253], 0, v[212:213]
	global_load_dwordx4 v[238:241], v[250:251], off offset:16
	global_load_dwordx4 v[234:237], v[250:251], off
	v_lshl_add_u64 v[250:251], v[252:253], 0, v[210:211]
	global_load_dwordx4 v[246:249], v[250:251], off offset:16
	global_load_dwordx4 v[242:245], v[250:251], off
	global_store_dwordx4 v[8:9], v[36:39], off
	v_mov_b32_e32 v45, v44
	v_pk_mul_f32 v[2:3], v[30:31], v[44:45]
	v_pk_mul_f32 v[6:7], v[26:27], v[44:45]
	v_pk_mul_f32 v[4:5], v[32:33], v[44:45]
	v_pk_mul_f32 v[8:9], v[28:29], v[44:45]
	s_and_saveexec_b64 s[18:19], s[10:11]
	s_cbranch_execz .LBB0_449
	v_mov_b32_e32 v145, v1
	s_waitcnt vmcnt(7)
	v_pk_mul_f32 v[36:37], v[2:3], v[226:227] op_sel:[1, 1] op_sel_hi:[1, 0]
	s_nop 0
	v_pk_fma_f32 v[26:27], v[2:3], v[226:227], v[36:37] op_sel_hi:[0, 1, 1] neg_lo:[0, 0, 1] neg_hi:[0, 0, 1]
	v_pk_fma_f32 v[2:3], v[2:3], v[226:227], v[36:37] op_sel_hi:[0, 1, 1]
	v_pk_mul_f32 v[36:37], v[4:5], v[228:229] op_sel:[1, 1] op_sel_hi:[1, 0]
	v_mul_f32_e32 v2, v9, v233
	v_pk_fma_f32 v[28:29], v[4:5], v[228:229], v[36:37] op_sel_hi:[0, 1, 1] neg_lo:[0, 0, 1] neg_hi:[0, 0, 1]
	v_pk_fma_f32 v[4:5], v[4:5], v[228:229], v[36:37] op_sel_hi:[0, 1, 1]
	v_pk_mul_f32 v[36:37], v[6:7], v[230:231] op_sel:[1, 1] op_sel_hi:[1, 0]
	v_mov_b32_e32 v27, v3
	v_pk_fma_f32 v[30:31], v[6:7], v[230:231], v[36:37] op_sel_hi:[0, 1, 1] neg_lo:[0, 0, 1] neg_hi:[0, 0, 1]
	v_pk_fma_f32 v[6:7], v[6:7], v[230:231], v[36:37] op_sel_hi:[0, 1, 1]
	v_pk_fma_f32 v[32:33], v[8:9], v[232:233], v[2:3] op_sel_hi:[1, 1, 0] neg_lo:[0, 0, 1] neg_hi:[0, 0, 1]
	v_mul_f32_e32 v2, v9, v232
	v_pk_fma_f32 v[8:9], v[8:9], v[232:233], v[2:3] op_sel:[0, 1, 0] op_sel_hi:[1, 0, 0]
	v_mov_b32_e32 v29, v5
	v_mov_b32_e32 v31, v7
	v_mov_b32_e32 v33, v8
	v_mov_b64_e32 v[2:3], v[26:27]
	v_mov_b64_e32 v[4:5], v[28:29]
	v_mov_b64_e32 v[6:7], v[30:31]
	v_mov_b64_e32 v[8:9], v[32:33]

; __device__ __forceinline__ float silu_f(float x) { return x * __builtin_amdgcn_rcpf(1.0f + __builtin_amdgcn_exp2f(-x * 1.4426950408889634f)); }
; __device__ __forceinline__ void rope8(float (&v)[8], const tab_t* tp) {
;     const f32x4 t0 = *(const f32x4*)tp, t1 = *(const f32x4*)(tp + 2);
;     const float c[4] = {t0[0], t0[2], t1[0], t1[2]}, s[4] = {t0[1], t0[3], t1[1], t1[3]};
; #pragma unroll
;     for (int j = 0; j < 4; ++j) { const float a = v[2 * j], b = v[2 * j + 1]; v[2 * j] = a * c[j] - b * s[j]; v[2 * j + 1] = b * c[j] + a * s[j]; }
; }
;     __device__ __forceinline__ void operator()(const f32x4 (&acc)[2][2][4][2], const Unit& u, int wr, int wc, int fr, int fq) const {
;     ...
;                 const int row = row0 + ai * HALF + m * 16;
;                 const float r = __builtin_amdgcn_rsqf(sum_parts<8>(ssq_h + (size_t)row * 32) * (1.0f / 2048.0f) + 1e-6f);
; #pragma unroll
;                 for (int bj = 0; bj < 2; ++bj) {
;                     float v[8];
; #pragma unroll
;                     for (int e = 0; e < 4; ++e) { v[e] = acc[ai][bj][m][0][e] * r; v[4 + e] = acc[ai][bj][m][1][e] * r; }
;                     if (tab[bj] >= 0) rope8(v, TAB + (size_t)row * NTAB + tab[bj]);
;                     if (act[bj]) {
; #pragma unroll
;                         for (int e = 0; e < 8; ++e) v[e] = silu_f(v[e]);
;                     }
; #pragma unroll
;                     for (int e = 0; e < 8; ++e) v[e] *= sc[bj];
;                     if (ssq[bj]) { float s = 0.f;
; #pragma unroll
;                         for (int e = 0; e < 8; ++e) s += v[e] * v[e];
;                         s += __shfl_xor(s, 16); s += __shfl_xor(s, 32);
;                         if (fq == 0) ssq[bj][(size_t)row * sld[bj]] = s; }
;                     store8(dst[bj] + (size_t)row * ld[bj], v);
.LBB0_455:
	v_mul_lo_u32 v7, s93, v42
	v_mul_lo_u32 v29, s92, v43
	s_waitcnt lgkmcnt(0)
	v_mad_u64_u32 v[8:9], s[18:19], s92, v42, 0
	v_add3_u32 v9, v9, v29, v7
	v_lshl_add_u64 v[8:9], v[8:9], 1, v[122:123]
	v_cvt_pk_bf16_f32 v26, v26, v28
	v_cvt_pk_bf16_f32 v27, v4, v27
	v_cvt_pk_bf16_f32 v28, v3, v5
	v_cvt_pk_bf16_f32 v29, v2, v6
	global_store_dwordx4 v[8:9], v[26:29], off
	s_nop 1
	v_add_u32_e32 v26, 0xb0, v146
	v_ashrrev_i32_e32 v27, 31, v26
	v_mad_i64_i32 v[30:31], s[18:19], v26, s1, 0
	v_mov_b32_e32 v28, v175
	s_nop 0
	v_pk_mul_f32 v[2:3], v[22:23], v[28:29] op_sel_hi:[1,0]
	v_pk_mul_f32 v[6:7], v[18:19], v[28:29] op_sel_hi:[1,0]
	v_pk_mul_f32 v[4:5], v[24:25], v[28:29] op_sel_hi:[1,0]
	v_pk_mul_f32 v[8:9], v[20:21], v[28:29] op_sel_hi:[1,0]
	v_lshl_add_u64 v[18:19], s[70:71], 0, v[30:31]
	s_and_saveexec_b64 s[18:19], s[6:7]
	s_cbranch_execz .LBB0_457
	s_waitcnt vmcnt(4)
	v_mul_f32_e32 v0, v9, v241
	v_pk_mul_f32 v[24:25], v[2:3], v[234:235] op_sel:[1, 1] op_sel_hi:[1, 0]
	v_pk_fma_f32 v[36:37], v[8:9], v[240:241], v[0:1] op_sel_hi:[1, 1, 0] neg_lo:[0, 0, 1] neg_hi:[0, 0, 1]
	v_pk_fma_f32 v[30:31], v[2:3], v[234:235], v[24:25] op_sel_hi:[0, 1, 1] neg_lo:[0, 0, 1] neg_hi:[0, 0, 1]
	v_pk_fma_f32 v[2:3], v[2:3], v[234:235], v[24:25] op_sel_hi:[0, 1, 1]
	v_pk_mul_f32 v[24:25], v[4:5], v[236:237] op_sel:[1, 1] op_sel_hi:[1, 0]
	v_mul_f32_e32 v0, v9, v240
	v_pk_fma_f32 v[32:33], v[4:5], v[236:237], v[24:25] op_sel_hi:[0, 1, 1] neg_lo:[0, 0, 1] neg_hi:[0, 0, 1]
	v_pk_fma_f32 v[4:5], v[4:5], v[236:237], v[24:25] op_sel_hi:[0, 1, 1]
	v_pk_mul_f32 v[24:25], v[6:7], v[238:239] op_sel:[1, 1] op_sel_hi:[1, 0]
	v_pk_fma_f32 v[8:9], v[8:9], v[240:241], v[0:1] op_sel:[0, 1, 0] op_sel_hi:[1, 0, 0]
	v_pk_fma_f32 v[34:35], v[6:7], v[238:239], v[24:25] op_sel_hi:[0, 1, 1] neg_lo:[0, 0, 1] neg_hi:[0, 0, 1]
	v_pk_fma_f32 v[6:7], v[6:7], v[238:239], v[24:25] op_sel_hi:[0, 1, 1]
	v_mov_b32_e32 v31, v3
	v_mov_b32_e32 v33, v5
	v_mov_b32_e32 v35, v7
	v_mov_b32_e32 v37, v8
	v_mov_b64_e32 v[2:3], v[30:31]
	v_mov_b64_e32 v[4:5], v[32:33]
	v_mov_b64_e32 v[6:7], v[34:35]
	v_mov_b64_e32 v[8:9], v[36:37]

; __device__ __forceinline__ float silu_f(float x) { return x * __builtin_amdgcn_rcpf(1.0f + __builtin_amdgcn_exp2f(-x * 1.4426950408889634f)); }
; __device__ __forceinline__ void rope8(float (&v)[8], const tab_t* tp) {
;     const f32x4 t0 = *(const f32x4*)tp, t1 = *(const f32x4*)(tp + 2);
;     const float c[4] = {t0[0], t0[2], t1[0], t1[2]}, s[4] = {t0[1], t0[3], t1[1], t1[3]};
; #pragma unroll
;     for (int j = 0; j < 4; ++j) { const float a = v[2 * j], b = v[2 * j + 1]; v[2 * j] = a * c[j] - b * s[j]; v[2 * j + 1] = b * c[j] + a * s[j]; }
; }
;     __device__ __forceinline__ void operator()(const f32x4 (&acc)[2][2][4][2], const Unit& u, int wr, int wc, int fr, int fq) const {
;     ...
;                 for (int bj = 0; bj < 2; ++bj) {
;                     float v[8];
; #pragma unroll
;                     for (int e = 0; e < 4; ++e) { v[e] = acc[ai][bj][m][0][e] * r; v[4 + e] = acc[ai][bj][m][1][e] * r; }
;                     if (tab[bj] >= 0) rope8(v, TAB + (size_t)row * NTAB + tab[bj]);
;                     if (act[bj]) {
; #pragma unroll
;                         for (int e = 0; e < 8; ++e) v[e] = silu_f(v[e]);
;                     }
; #pragma unroll
;                     for (int e = 0; e < 8; ++e) v[e] *= sc[bj];
;                     if (ssq[bj]) { float s = 0.f;
; #pragma unroll
;                         for (int e = 0; e < 8; ++e) s += v[e] * v[e];
;                         s += __shfl_xor(s, 16); s += __shfl_xor(s, 32);
;                         if (fq == 0) ssq[bj][(size_t)row * sld[bj]] = s; }
;                     store8(dst[bj] + (size_t)row * ld[bj], v);
.LBB0_463:
	v_mul_lo_u32 v7, s91, v26
	v_mul_lo_u32 v22, s90, v27
	s_waitcnt lgkmcnt(0)
	v_mad_u64_u32 v[8:9], s[6:7], s90, v26, 0
	v_add3_u32 v9, v9, v22, v7
	v_lshl_add_u64 v[8:9], v[8:9], 1, v[148:149]
	v_cvt_pk_bf16_f32 v20, v20, v21
	v_cvt_pk_bf16_f32 v21, v3, v5
	v_cvt_pk_bf16_f32 v22, v2, v4
	v_cvt_pk_bf16_f32 v23, v0, v6
	global_store_dwordx4 v[8:9], v[20:23], off
	v_mov_b32_e32 v29, v28
	v_pk_mul_f32 v[2:3], v[14:15], v[28:29]
	v_pk_mul_f32 v[6:7], v[10:11], v[28:29]
	v_pk_mul_f32 v[4:5], v[16:17], v[28:29]
	v_pk_mul_f32 v[8:9], v[12:13], v[28:29]
	s_and_saveexec_b64 s[6:7], s[10:11]
	s_cbranch_execz .LBB0_465
	v_mov_b32_e32 v145, v1
	s_waitcnt vmcnt(3)
	v_mul_f32_e32 v0, v9, v249
	v_pk_mul_f32 v[20:21], v[2:3], v[242:243] op_sel:[1, 1] op_sel_hi:[1, 0]
	s_nop 0
	v_pk_fma_f32 v[10:11], v[2:3], v[242:243], v[20:21] op_sel_hi:[0, 1, 1] neg_lo:[0, 0, 1] neg_hi:[0, 0, 1]
	v_pk_fma_f32 v[2:3], v[2:3], v[242:243], v[20:21] op_sel_hi:[0, 1, 1]
	v_pk_mul_f32 v[20:21], v[4:5], v[244:245] op_sel:[1, 1] op_sel_hi:[1, 0]
	v_mov_b32_e32 v11, v3
	v_pk_fma_f32 v[12:13], v[4:5], v[244:245], v[20:21] op_sel_hi:[0, 1, 1] neg_lo:[0, 0, 1] neg_hi:[0, 0, 1]
	v_pk_fma_f32 v[4:5], v[4:5], v[244:245], v[20:21] op_sel_hi:[0, 1, 1]
	v_pk_mul_f32 v[20:21], v[6:7], v[246:247] op_sel:[1, 1] op_sel_hi:[1, 0]
	v_mov_b32_e32 v13, v5
	v_pk_fma_f32 v[14:15], v[6:7], v[246:247], v[20:21] op_sel_hi:[0, 1, 1] neg_lo:[0, 0, 1] neg_hi:[0, 0, 1]
	v_pk_fma_f32 v[6:7], v[6:7], v[246:247], v[20:21] op_sel_hi:[0, 1, 1]
	v_pk_fma_f32 v[16:17], v[8:9], v[248:249], v[0:1] op_sel_hi:[1, 1, 0] neg_lo:[0, 0, 1] neg_hi:[0, 0, 1]
	v_mul_f32_e32 v0, v9, v248
	v_pk_fma_f32 v[8:9], v[8:9], v[248:249], v[0:1] op_sel:[0, 1, 0] op_sel_hi:[1, 0, 0]
	v_mov_b32_e32 v15, v7
	v_mov_b32_e32 v17, v8
	v_mov_b64_e32 v[2:3], v[10:11]
	v_mov_b64_e32 v[4:5], v[12:13]
	v_mov_b64_e32 v[6:7], v[14:15]
	v_mov_b64_e32 v[8:9], v[16:17]

; #define PG8_BAR __builtin_amdgcn_s_barrier()
;     __device__ __forceinline__ void operator()(const f32x4 (&acc)[2][2][4][2], const Unit& u, int wr, int wc, int fr, int fq) const {
;     ...
;                     store8(dst[bj] + (size_t)row * ld[bj], v);
;                     asm volatile("" ::: "memory");
;                 }
;             }
; template <class Epi, class Sched, bool ALIGN_EPI = false, bool SP2 = false>
; __device__ __forceinline__ void gemm_phase(PG8_LAS unsigned char* lds, const Gemm g, const Sched& S, const Epi& E) {
;     ...
;         if constexpr (!Epi::AFTER_DRAIN) { E(acc, cur, wr, wc, fr, fq); S.done(cur); }
;         if (!has_next) break;
; #pragma unroll
;         for (int a = 0; a < 2; ++a)
; #pragma unroll
;             for (int b = 0; b < 2; ++b)
; #pragma unroll
;                 for (int m = 0; m < 4; ++m)
; #pragma unroll
;                     for (int n = 0; n < 2; ++n) acc[a][b][m][n] = (f32x4){0.f, 0.f, 0.f, 0.f};
;         cur = nxt; cA = nA; cB = nB; ++ui;
;         if constexpr (ALIGN_EPI) { if (wr == 1) PG8_BAR; }
;     }
.LBB0_471:
	v_mul_lo_u32 v7, s93, v26
	v_mul_lo_u32 v12, s92, v27
	s_waitcnt lgkmcnt(0)
	v_mad_u64_u32 v[8:9], s[4:5], s92, v26, 0
	v_add3_u32 v9, v9, v12, v7
	v_lshl_add_u64 v[12:13], v[8:9], 1, v[122:123]
	v_cvt_pk_bf16_f32 v8, v10, v11
	v_cvt_pk_bf16_f32 v9, v3, v5
	v_cvt_pk_bf16_f32 v10, v2, v4
	v_cvt_pk_bf16_f32 v11, v0, v6
	global_store_dwordx4 v[12:13], v[8:11], off
	s_waitcnt vmcnt(4)
	s_andn2_b64 vcc, exec, s[2:3]
	s_mov_b64 s[2:3], -1
	s_mov_b32 s92, s50
	s_cbranch_vccnz .LBB0_298
	v_readlane_b32 s2, v255, 7
	v_readlane_b32 s3, v255, 8
	s_andn2_b64 vcc, exec, s[2:3]
	s_cbranch_vccnz .LBB0_297
	s_barrier
	s_branch .LBB0_297
